# v8 + in-proj log-sigmoid epilogue without the never-taken denormal rescue around v_log (argument always in [1,2])
# baseline (speedup 1.0000x reference)
; __device__ __forceinline__ unsigned cvt_pk_bf16(float lo, float hi) { unsigned r; asm volatile("v_cvt_pk_bf16_f32 %0, %1, %2" : "=v"(r) : "v"(lo), "v"(hi)); return r; }
;     __device__ __forceinline__ void operator()(const AccT& acc, const pg8::Unit& u, int wr, int wc, int fr, int fq) const {
;     ...
;         if (pn >= 22) {
; #pragma unroll
;             for (int ai = 0; ai < 2; ++ai)
; #pragma unroll
;                 for (int m = 0; m < 4; ++m) {
;                     const int row = row0 + ai * 128 + m * 16; const float rs = rsv[ai * 4 + m];
; #pragma unroll
;                     for (int bj = 0; bj < 2; ++bj) {
;                         const int cg = coff + ct + bj * 128;
;                         const f32x4 b0 = *(const f32x4*)(blr_b + cg), b1 = *(const f32x4*)(blr_b + cg + 4);
;                         f32x4 x0 = acc[ai][bj][m][0] * rs + b0, x1 = acc[ai][bj][m][1] * rs + b1;
; #pragma unroll
;                         for (int j = 0; j < 4; ++j) { x0[j] = (fminf(x0[j], 0.f) - __logf(1.f + __expf(-fabsf(x0[j])))) * (1.f / 16.f); x1[j] = (fminf(x1[j], 0.f) - __logf(1.f + __expf(-fabsf(x1[j])))) * (1.f / 16.f); }
;                         u32x4 w; w.x = cvt_pk_bf16(x0[0], x0[1]); w.y = cvt_pk_bf16(x0[2], x0[3]); w.z = cvt_pk_bf16(x1[0], x1[1]); w.w = cvt_pk_bf16(x1[2], x1[3]);
;                         *(u32x4*)(base + (size_t)row * 512 + cg) = w;
.LBB0_232:
	s_and_b64 vcc, exec, s[6:7]
	s_cbranch_vccz .LBB0_231
	v_add_u32_e32 v130, s48, v148
	v_readlane_b32 s60, v250, 20
	v_lshlrev_b64 v[128:129], 10, v[170:171]
	v_ashrrev_i32_e32 v131, 31, v130
	v_readlane_b32 s64, v250, 24
	v_readlane_b32 s65, v250, 25
	v_lshl_add_u64 v[132:133], s[58:59], 0, v[128:129]
	v_readlane_b32 s61, v250, 21
	v_lshl_add_u64 v[128:129], v[130:131], 2, s[64:65]
	global_load_dwordx4 v[178:181], v[128:129], off offset:16
	global_load_dwordx4 v[182:185], v[128:129], off
	v_readlane_b32 s62, v250, 22
	v_readlane_b32 s63, v250, 23
	v_readlane_b32 s66, v250, 26
	v_readlane_b32 s67, v250, 27
	v_readlane_b32 s68, v250, 28
	v_readlane_b32 s69, v250, 29
	v_readlane_b32 s70, v250, 30
	v_readlane_b32 s71, v250, 31
	v_readlane_b32 s72, v250, 32
	v_readlane_b32 s73, v250, 33
	v_readlane_b32 s74, v250, 34
	v_readlane_b32 s75, v250, 35
	s_waitcnt vmcnt(0)
	v_pk_fma_f32 v[134:135], v[120:121], v[176:177], v[178:179] op_sel_hi:[1,0,1]
	v_pk_fma_f32 v[124:125], v[124:125], v[176:177], v[182:183] op_sel_hi:[1,0,1]
	v_pk_fma_f32 v[126:127], v[126:127], v[176:177], v[184:185] op_sel_hi:[1,0,1]
	v_mul_f32_e64 v121, |v124|, s25
	v_exp_f32_e32 v121, v121
	v_min_f32_e32 v120, 0, v124
	v_pk_fma_f32 v[122:123], v[122:123], v[176:177], v[180:181] op_sel_hi:[1,0,1]
	v_add_f32_e32 v121, 1.0, v121
	v_log_f32_e32 v121, v121
	s_nop 0
	v_mul_f32_e32 v124, 0x3f317217, v121
	v_fma_f32 v124, v121, s23, -v124
	v_fmac_f32_e32 v124, 0x3377d1cf, v121
	v_fmac_f32_e32 v124, 0x3f317217, v121
	v_mov_b32_e32 v121, v124
	v_mul_f32_e64 v124, |v134|, s25
	v_exp_f32_e32 v124, v124
	v_sub_f32_e32 v120, v120, v121
	v_min_f32_e32 v121, 0, v134
	v_mul_f32_e32 v120, 0x3d800000, v120
	v_add_f32_e32 v124, 1.0, v124
	v_log_f32_e32 v124, v124
	s_nop 0
	v_mul_f32_e32 v134, 0x3f317217, v124
	v_fma_f32 v134, v124, s23, -v134
	v_fmac_f32_e32 v134, 0x3377d1cf, v124
	v_fmac_f32_e32 v134, 0x3f317217, v124
	v_mov_b32_e32 v124, v134
	v_sub_f32_e32 v121, v121, v124
	v_min_f32_e32 v124, 0, v125
	v_mul_f32_e64 v125, |v125|, s25
	v_exp_f32_e32 v125, v125
	v_mul_f32_e32 v121, 0x3d800000, v121
	v_add_f32_e32 v125, 1.0, v125
	v_log_f32_e32 v125, v125
	s_nop 0
	v_mul_f32_e32 v134, 0x3f317217, v125
	v_fma_f32 v134, v125, s23, -v134
	v_fmac_f32_e32 v134, 0x3377d1cf, v125
	v_fmac_f32_e32 v134, 0x3f317217, v125
	v_mov_b32_e32 v125, v134
	v_mul_f32_e64 v134, |v135|, s25
	v_exp_f32_e32 v134, v134
	v_sub_f32_e32 v124, v124, v125
	v_min_f32_e32 v125, 0, v135
	v_mul_f32_e32 v124, 0x3d800000, v124
	v_add_f32_e32 v134, 1.0, v134
	v_cvt_pk_bf16_f32 v178, v120, v124
	v_log_f32_e32 v134, v134
	s_nop 0
	v_mul_f32_e32 v135, 0x3f317217, v134
	v_fma_f32 v135, v134, s23, -v135
	v_fmac_f32_e32 v135, 0x3377d1cf, v134
	v_fmac_f32_e32 v135, 0x3f317217, v134
	v_mov_b32_e32 v134, v135
	v_sub_f32_e32 v125, v125, v134
	v_min_f32_e32 v134, 0, v126
	v_mul_f32_e64 v126, |v126|, s25
	v_exp_f32_e32 v126, v126
	v_mul_f32_e32 v125, 0x3d800000, v125
	v_add_f32_e32 v126, 1.0, v126
	v_log_f32_e32 v126, v126
	s_nop 0
	v_mul_f32_e32 v135, 0x3f317217, v126
	v_fma_f32 v135, v126, s23, -v135
	v_fmac_f32_e32 v135, 0x3377d1cf, v126
	v_fmac_f32_e32 v135, 0x3f317217, v126
	v_mov_b32_e32 v126, v135
	v_sub_f32_e32 v126, v134, v126
	v_min_f32_e32 v134, 0, v122
	v_mul_f32_e64 v122, |v122|, s25
	v_exp_f32_e32 v122, v122
	v_mul_f32_e32 v126, 0x3d800000, v126
	v_add_f32_e32 v122, 1.0, v122
	v_log_f32_e32 v122, v122
	s_nop 0
	v_mul_f32_e32 v135, 0x3f317217, v122
	v_fma_f32 v135, v122, s23, -v135
	v_fmac_f32_e32 v135, 0x3377d1cf, v122
	v_fmac_f32_e32 v135, 0x3f317217, v122
	v_mov_b32_e32 v122, v135
	v_sub_f32_e32 v122, v134, v122
	v_min_f32_e32 v134, 0, v127
	v_mul_f32_e64 v127, |v127|, s25
	v_exp_f32_e32 v127, v127
	v_mul_f32_e32 v122, 0x3d800000, v122
	v_add_f32_e32 v127, 1.0, v127
	v_log_f32_e32 v127, v127
	s_nop 0
	v_mul_f32_e32 v135, 0x3f317217, v127
	v_fma_f32 v135, v127, s23, -v135
	v_fmac_f32_e32 v135, 0x3377d1cf, v127
	v_fmac_f32_e32 v135, 0x3f317217, v127
	v_mov_b32_e32 v127, v135
	v_sub_f32_e32 v127, v134, v127
	v_min_f32_e32 v134, 0, v123
	v_mul_f32_e64 v123, |v123|, s25
	v_exp_f32_e32 v123, v123
	v_mul_f32_e32 v127, 0x3d800000, v127
	v_cvt_pk_bf16_f32 v179, v126, v127
	v_cvt_pk_bf16_f32 v180, v121, v125
	v_add_f32_e32 v123, 1.0, v123
	v_log_f32_e32 v123, v123
	s_nop 0
	v_mul_f32_e32 v135, 0x3f317217, v123
	v_fma_f32 v135, v123, s23, -v135
	v_fmac_f32_e32 v135, 0x3377d1cf, v123
	v_fmac_f32_e32 v135, 0x3f317217, v123
	v_mov_b32_e32 v123, v135
	v_sub_f32_e32 v123, v134, v123
	v_mul_f32_e32 v123, 0x3d800000, v123
	v_cvt_pk_bf16_f32 v181, v122, v123
	v_lshlrev_b64 v[122:123], 1, v[130:131]
	v_lshl_add_u64 v[120:121], v[132:133], 0, v[122:123]
	global_store_dwordx4 v[120:121], v[178:181], off
	global_load_dwordx4 v[124:127], v[128:129], off offset:528
	global_load_dwordx4 v[130:133], v[128:129], off offset:512
	s_waitcnt vmcnt(1)
	v_pk_fma_f32 v[112:113], v[112:113], v[176:177], v[124:125] op_sel_hi:[1,0,1]
	s_waitcnt vmcnt(0)
; __device__ __forceinline__ unsigned cvt_pk_bf16(float lo, float hi) { unsigned r; asm volatile("v_cvt_pk_bf16_f32 %0, %1, %2" : "=v"(r) : "v"(lo), "v"(hi)); return r; }
;     __device__ __forceinline__ void operator()(const AccT& acc, const pg8::Unit& u, int wr, int wc, int fr, int fq) const {
;     ...
;         if (pn >= 22) {
; #pragma unroll
;             for (int ai = 0; ai < 2; ++ai)
; #pragma unroll
;                 for (int m = 0; m < 4; ++m) {
;                     const int row = row0 + ai * 128 + m * 16; const float rs = rsv[ai * 4 + m];
; #pragma unroll
;                     for (int bj = 0; bj < 2; ++bj) {
;                         const int cg = coff + ct + bj * 128;
;                         const f32x4 b0 = *(const f32x4*)(blr_b + cg), b1 = *(const f32x4*)(blr_b + cg + 4);
;                         f32x4 x0 = acc[ai][bj][m][0] * rs + b0, x1 = acc[ai][bj][m][1] * rs + b1;
; #pragma unroll
;                         for (int j = 0; j < 4; ++j) { x0[j] = (fminf(x0[j], 0.f) - __logf(1.f + __expf(-fabsf(x0[j])))) * (1.f / 16.f); x1[j] = (fminf(x1[j], 0.f) - __logf(1.f + __expf(-fabsf(x1[j])))) * (1.f / 16.f); }
;                         u32x4 w; w.x = cvt_pk_bf16(x0[0], x0[1]); w.y = cvt_pk_bf16(x0[2], x0[3]); w.z = cvt_pk_bf16(x1[0], x1[1]); w.w = cvt_pk_bf16(x1[2], x1[3]);
;                         *(u32x4*)(base + (size_t)row * 512 + cg) = w;
	v_pk_fma_f32 v[116:117], v[116:117], v[176:177], v[130:131] op_sel_hi:[1,0,1]
	v_pk_fma_f32 v[118:119], v[118:119], v[176:177], v[132:133] op_sel_hi:[1,0,1]
	v_min_f32_e32 v124, 0, v116
	v_mul_f32_e64 v116, |v116|, s25
	v_exp_f32_e32 v116, v116
	v_pk_fma_f32 v[114:115], v[114:115], v[176:177], v[126:127] op_sel_hi:[1,0,1]
	v_add_f32_e32 v116, 1.0, v116
	v_log_f32_e32 v116, v116
	s_nop 0
	v_mul_f32_e32 v125, 0x3f317217, v116
	v_fma_f32 v125, v116, s23, -v125
	v_fmac_f32_e32 v125, 0x3377d1cf, v116
	v_fmac_f32_e32 v125, 0x3f317217, v116
	v_mov_b32_e32 v116, v125
	v_sub_f32_e32 v116, v124, v116
	v_min_f32_e32 v124, 0, v112
	v_mul_f32_e64 v112, |v112|, s25
	v_exp_f32_e32 v112, v112
	v_mul_f32_e32 v116, 0x3d800000, v116
	v_add_f32_e32 v112, 1.0, v112
	v_log_f32_e32 v112, v112
	s_nop 0
	v_mul_f32_e32 v125, 0x3f317217, v112
	v_fma_f32 v125, v112, s23, -v125
	v_fmac_f32_e32 v125, 0x3377d1cf, v112
	v_fmac_f32_e32 v125, 0x3f317217, v112
	v_mov_b32_e32 v112, v125
	v_sub_f32_e32 v112, v124, v112
	v_min_f32_e32 v124, 0, v117
	v_mul_f32_e64 v117, |v117|, s25
	v_exp_f32_e32 v117, v117
	v_mul_f32_e32 v112, 0x3d800000, v112
	v_add_f32_e32 v117, 1.0, v117
	v_log_f32_e32 v117, v117
	s_nop 0
	v_mul_f32_e32 v125, 0x3f317217, v117
	v_fma_f32 v125, v117, s23, -v125
	v_fmac_f32_e32 v125, 0x3377d1cf, v117
	v_fmac_f32_e32 v125, 0x3f317217, v117
	v_mov_b32_e32 v117, v125
	v_sub_f32_e32 v117, v124, v117
	v_min_f32_e32 v124, 0, v113
	v_mul_f32_e64 v113, |v113|, s25
	v_exp_f32_e32 v113, v113
	v_mul_f32_e32 v117, 0x3d800000, v117
	v_add_f32_e32 v113, 1.0, v113
	v_log_f32_e32 v113, v113
	s_nop 0
	v_mul_f32_e32 v125, 0x3f317217, v113
	v_fma_f32 v125, v113, s23, -v125
	v_fmac_f32_e32 v125, 0x3377d1cf, v113
	v_fmac_f32_e32 v125, 0x3f317217, v113
	v_mov_b32_e32 v113, v125
	v_sub_f32_e32 v113, v124, v113
	v_min_f32_e32 v124, 0, v118
	v_mul_f32_e64 v118, |v118|, s25
	v_exp_f32_e32 v118, v118
	v_mul_f32_e32 v113, 0x3d800000, v113
	v_add_f32_e32 v118, 1.0, v118
	v_log_f32_e32 v118, v118
	s_nop 0
	v_mul_f32_e32 v125, 0x3f317217, v118
	v_fma_f32 v125, v118, s23, -v125
	v_fmac_f32_e32 v125, 0x3377d1cf, v118
	v_fmac_f32_e32 v125, 0x3f317217, v118
	v_mov_b32_e32 v118, v125
	v_sub_f32_e32 v118, v124, v118
	v_min_f32_e32 v124, 0, v114
	v_mul_f32_e64 v114, |v114|, s25
	v_exp_f32_e32 v114, v114
	v_mul_f32_e32 v118, 0x3d800000, v118
	v_add_f32_e32 v114, 1.0, v114
	v_log_f32_e32 v114, v114
	s_nop 0
	v_mul_f32_e32 v125, 0x3f317217, v114
	v_fma_f32 v125, v114, s23, -v125
	v_fmac_f32_e32 v125, 0x3377d1cf, v114
	v_fmac_f32_e32 v125, 0x3f317217, v114
	v_mov_b32_e32 v114, v125
	v_sub_f32_e32 v114, v124, v114
	v_mul_f32_e32 v124, 0x3d800000, v114
	v_min_f32_e32 v114, 0, v119
	v_mul_f32_e64 v119, |v119|, s25
	v_exp_f32_e32 v119, v119
	s_nop 0
	v_add_f32_e32 v119, 1.0, v119
	v_log_f32_e32 v119, v119
	s_nop 0
	v_mul_f32_e32 v125, 0x3f317217, v119
	v_fma_f32 v125, v119, s23, -v125
	v_fmac_f32_e32 v125, 0x3377d1cf, v119
	v_fmac_f32_e32 v125, 0x3f317217, v119
	v_mov_b32_e32 v119, v125
	v_sub_f32_e32 v114, v114, v119
	v_mul_f32_e32 v119, 0x3d800000, v114
	v_min_f32_e32 v114, 0, v115
	v_mul_f32_e64 v115, |v115|, s25
	v_exp_f32_e32 v115, v115
	s_nop 0
	v_add_f32_e32 v115, 1.0, v115
	v_log_f32_e32 v115, v115
	s_nop 0
	v_mul_f32_e32 v125, 0x3f317217, v115
	v_fma_f32 v125, v115, s23, -v125
	v_fmac_f32_e32 v125, 0x3377d1cf, v115
	v_fmac_f32_e32 v125, 0x3f317217, v115
	v_mov_b32_e32 v115, v125
	v_sub_f32_e32 v114, v114, v115
	v_mul_f32_e32 v125, 0x3d800000, v114
	v_cvt_pk_bf16_f32 v114, v116, v117
	v_cvt_pk_bf16_f32 v115, v118, v119
	v_cvt_pk_bf16_f32 v116, v112, v113
	v_cvt_pk_bf16_f32 v117, v124, v125
	global_store_dwordx4 v[120:121], v[114:117], off offset:256
	global_load_dwordx4 v[114:117], v[128:129], off offset:16
	s_nop 0
	global_load_dwordx4 v[124:127], v[128:129], off
	v_or_b32_e32 v112, 16, v170
	v_ashrrev_i32_e32 v113, 31, v112
	v_lshlrev_b64 v[112:113], 10, v[112:113]
	v_lshl_add_u64 v[112:113], s[58:59], 0, v[112:113]
	s_waitcnt vmcnt(1)
	v_pk_fma_f32 v[114:115], v[104:105], v[174:175], v[114:115] op_sel_hi:[1,0,1]
	s_waitcnt vmcnt(0)
	v_pk_fma_f32 v[108:109], v[108:109], v[174:175], v[124:125] op_sel_hi:[1,0,1]
	v_pk_fma_f32 v[110:111], v[110:111], v[174:175], v[126:127] op_sel_hi:[1,0,1]
	v_mul_f32_e64 v105, |v108|, s25
	v_exp_f32_e32 v105, v105
	v_min_f32_e32 v104, 0, v108
	v_pk_fma_f32 v[106:107], v[106:107], v[174:175], v[116:117] op_sel_hi:[1,0,1]
	v_add_f32_e32 v105, 1.0, v105
	v_log_f32_e32 v105, v105
	s_nop 0
	v_mul_f32_e32 v108, 0x3f317217, v105
	v_fma_f32 v108, v105, s23, -v108
	v_fmac_f32_e32 v108, 0x3377d1cf, v105
	v_fmac_f32_e32 v108, 0x3f317217, v105
	v_mov_b32_e32 v105, v108
	v_mul_f32_e64 v108, |v114|, s25
	v_exp_f32_e32 v108, v108
	v_sub_f32_e32 v104, v104, v105
	v_min_f32_e32 v105, 0, v114
	v_mul_f32_e32 v104, 0x3d800000, v104
	v_add_f32_e32 v108, 1.0, v108
	v_log_f32_e32 v108, v108
	s_nop 0
	v_mul_f32_e32 v114, 0x3f317217, v108
	v_fma_f32 v114, v108, s23, -v114
	v_fmac_f32_e32 v114, 0x3377d1cf, v108
	v_fmac_f32_e32 v114, 0x3f317217, v108
	v_mov_b32_e32 v108, v114
	v_sub_f32_e32 v105, v105, v108
	v_min_f32_e32 v108, 0, v109
	v_mul_f32_e64 v109, |v109|, s25
	v_exp_f32_e32 v109, v109
	v_mul_f32_e32 v105, 0x3d800000, v105
	v_add_f32_e32 v109, 1.0, v109
	v_log_f32_e32 v109, v109
	s_nop 0
	v_mul_f32_e32 v114, 0x3f317217, v109
	v_fma_f32 v114, v109, s23, -v114
	v_fmac_f32_e32 v114, 0x3377d1cf, v109
	v_fmac_f32_e32 v114, 0x3f317217, v109
	v_mov_b32_e32 v109, v114
	v_mul_f32_e64 v114, |v115|, s25
	v_exp_f32_e32 v114, v114
	v_sub_f32_e32 v108, v108, v109
	v_min_f32_e32 v109, 0, v115
	v_mul_f32_e32 v108, 0x3d800000, v108
	v_add_f32_e32 v114, 1.0, v114
	v_log_f32_e32 v114, v114
	s_nop 0
; __device__ __forceinline__ unsigned cvt_pk_bf16(float lo, float hi) { unsigned r; asm volatile("v_cvt_pk_bf16_f32 %0, %1, %2" : "=v"(r) : "v"(lo), "v"(hi)); return r; }
;     __device__ __forceinline__ void operator()(const AccT& acc, const pg8::Unit& u, int wr, int wc, int fr, int fq) const {
;     ...
;             for (int ai = 0; ai < 2; ++ai)
; #pragma unroll
;                 for (int m = 0; m < 4; ++m) {
;                     const int row = row0 + ai * 128 + m * 16; const float rs = rsv[ai * 4 + m];
; #pragma unroll
;                     for (int bj = 0; bj < 2; ++bj) {
;                         const int cg = coff + ct + bj * 128;
;                         const f32x4 b0 = *(const f32x4*)(blr_b + cg), b1 = *(const f32x4*)(blr_b + cg + 4);
;                         f32x4 x0 = acc[ai][bj][m][0] * rs + b0, x1 = acc[ai][bj][m][1] * rs + b1;
; #pragma unroll
;                         for (int j = 0; j < 4; ++j) { x0[j] = (fminf(x0[j], 0.f) - __logf(1.f + __expf(-fabsf(x0[j])))) * (1.f / 16.f); x1[j] = (fminf(x1[j], 0.f) - __logf(1.f + __expf(-fabsf(x1[j])))) * (1.f / 16.f); }
;                         u32x4 w; w.x = cvt_pk_bf16(x0[0], x0[1]); w.y = cvt_pk_bf16(x0[2], x0[3]); w.z = cvt_pk_bf16(x1[0], x1[1]); w.w = cvt_pk_bf16(x1[2], x1[3]);
;                         *(u32x4*)(base + (size_t)row * 512 + cg) = w;
	v_mul_f32_e32 v115, 0x3f317217, v114
	v_fma_f32 v115, v114, s23, -v115
	v_fmac_f32_e32 v115, 0x3377d1cf, v114
	v_fmac_f32_e32 v115, 0x3f317217, v114
	v_mov_b32_e32 v114, v115
	v_sub_f32_e32 v109, v109, v114
	v_min_f32_e32 v114, 0, v110
	v_mul_f32_e64 v110, |v110|, s25
	v_exp_f32_e32 v110, v110
	v_mul_f32_e32 v109, 0x3d800000, v109
	v_add_f32_e32 v110, 1.0, v110
	v_log_f32_e32 v110, v110
	s_nop 0
	v_mul_f32_e32 v115, 0x3f317217, v110
	v_fma_f32 v115, v110, s23, -v115
	v_fmac_f32_e32 v115, 0x3377d1cf, v110
	v_fmac_f32_e32 v115, 0x3f317217, v110
	v_mov_b32_e32 v110, v115
	v_sub_f32_e32 v110, v114, v110
	v_min_f32_e32 v114, 0, v106
	v_mul_f32_e64 v106, |v106|, s25
	v_exp_f32_e32 v106, v106
	v_mul_f32_e32 v110, 0x3d800000, v110
	v_add_f32_e32 v106, 1.0, v106
	v_log_f32_e32 v106, v106
	s_nop 0
	v_mul_f32_e32 v115, 0x3f317217, v106
	v_fma_f32 v115, v106, s23, -v115
	v_fmac_f32_e32 v115, 0x3377d1cf, v106
	v_fmac_f32_e32 v115, 0x3f317217, v106
	v_mov_b32_e32 v106, v115
	v_sub_f32_e32 v106, v114, v106
	v_mul_f32_e32 v114, 0x3d800000, v106
	v_min_f32_e32 v106, 0, v111
	v_mul_f32_e64 v111, |v111|, s25
	v_exp_f32_e32 v111, v111
	s_nop 0
	v_add_f32_e32 v111, 1.0, v111
	v_log_f32_e32 v111, v111
	s_nop 0
	v_mul_f32_e32 v115, 0x3f317217, v111
	v_fma_f32 v115, v111, s23, -v115
	v_fmac_f32_e32 v115, 0x3377d1cf, v111
	v_fmac_f32_e32 v115, 0x3f317217, v111
	v_mov_b32_e32 v111, v115
	v_sub_f32_e32 v106, v106, v111
	v_mul_f32_e32 v111, 0x3d800000, v106
	v_min_f32_e32 v106, 0, v107
	v_mul_f32_e64 v107, |v107|, s25
	v_exp_f32_e32 v107, v107
	s_nop 0
	v_add_f32_e32 v107, 1.0, v107
	v_log_f32_e32 v107, v107
	s_nop 0
	v_mul_f32_e32 v115, 0x3f317217, v107
	v_fma_f32 v115, v107, s23, -v115
	v_fmac_f32_e32 v115, 0x3377d1cf, v107
	v_fmac_f32_e32 v115, 0x3f317217, v107
	v_mov_b32_e32 v107, v115
	v_sub_f32_e32 v106, v106, v107
	v_mul_f32_e32 v115, 0x3d800000, v106
	v_cvt_pk_bf16_f32 v106, v104, v108
	v_cvt_pk_bf16_f32 v107, v110, v111
	v_cvt_pk_bf16_f32 v108, v105, v109
	v_lshl_add_u64 v[104:105], v[112:113], 0, v[122:123]
	v_cvt_pk_bf16_f32 v109, v114, v115
	global_store_dwordx4 v[104:105], v[106:109], off
	global_load_dwordx4 v[106:109], v[128:129], off offset:528
	s_nop 0
	global_load_dwordx4 v[110:113], v[128:129], off offset:512
	s_waitcnt vmcnt(1)
	v_pk_fma_f32 v[106:107], v[96:97], v[174:175], v[106:107] op_sel_hi:[1,0,1]
	s_waitcnt vmcnt(0)
	v_pk_fma_f32 v[100:101], v[100:101], v[174:175], v[110:111] op_sel_hi:[1,0,1]
	v_pk_fma_f32 v[102:103], v[102:103], v[174:175], v[112:113] op_sel_hi:[1,0,1]
	v_mul_f32_e64 v97, |v100|, s25
	v_exp_f32_e32 v97, v97
	v_min_f32_e32 v96, 0, v100
	v_pk_fma_f32 v[98:99], v[98:99], v[174:175], v[108:109] op_sel_hi:[1,0,1]
	v_add_f32_e32 v97, 1.0, v97
	v_log_f32_e32 v97, v97
	s_nop 0
	v_mul_f32_e32 v100, 0x3f317217, v97
	v_fma_f32 v100, v97, s23, -v100
	v_fmac_f32_e32 v100, 0x3377d1cf, v97
	v_fmac_f32_e32 v100, 0x3f317217, v97
	v_mov_b32_e32 v97, v100
	v_mul_f32_e64 v100, |v106|, s25
	v_exp_f32_e32 v100, v100
	v_sub_f32_e32 v96, v96, v97
	v_min_f32_e32 v97, 0, v106
	v_mul_f32_e32 v96, 0x3d800000, v96
	v_add_f32_e32 v100, 1.0, v100
	v_log_f32_e32 v100, v100
	s_nop 0
	v_mul_f32_e32 v106, 0x3f317217, v100
	v_fma_f32 v106, v100, s23, -v106
	v_fmac_f32_e32 v106, 0x3377d1cf, v100
	v_fmac_f32_e32 v106, 0x3f317217, v100
	v_mov_b32_e32 v100, v106
	v_sub_f32_e32 v97, v97, v100
	v_mul_f32_e32 v100, 0x3d800000, v97
	v_min_f32_e32 v97, 0, v101
	v_mul_f32_e64 v101, |v101|, s25
	v_exp_f32_e32 v101, v101
	s_nop 0
	v_add_f32_e32 v101, 1.0, v101
	v_log_f32_e32 v101, v101
	s_nop 0
	v_mul_f32_e32 v106, 0x3f317217, v101
	v_fma_f32 v106, v101, s23, -v106
	v_fmac_f32_e32 v106, 0x3377d1cf, v101
	v_fmac_f32_e32 v106, 0x3f317217, v101
	v_mov_b32_e32 v101, v106
	v_mul_f32_e64 v106, |v107|, s25
	v_exp_f32_e32 v106, v106
	v_sub_f32_e32 v97, v97, v101
	v_min_f32_e32 v101, 0, v107
	v_mul_f32_e32 v97, 0x3d800000, v97
	v_add_f32_e32 v106, 1.0, v106
	v_cvt_pk_bf16_f32 v96, v96, v97
	v_log_f32_e32 v106, v106
	s_nop 0
	v_mul_f32_e32 v107, 0x3f317217, v106
	v_fma_f32 v107, v106, s23, -v107
	v_fmac_f32_e32 v107, 0x3377d1cf, v106
	v_fmac_f32_e32 v107, 0x3f317217, v106
	v_mov_b32_e32 v106, v107
	v_sub_f32_e32 v101, v101, v106
	v_min_f32_e32 v106, 0, v102
	v_mul_f32_e64 v102, |v102|, s25
	v_exp_f32_e32 v102, v102
	v_mul_f32_e32 v101, 0x3d800000, v101
	v_add_f32_e32 v102, 1.0, v102
	v_log_f32_e32 v102, v102
	s_nop 0
	v_mul_f32_e32 v107, 0x3f317217, v102
	v_fma_f32 v107, v102, s23, -v107
	v_fmac_f32_e32 v107, 0x3377d1cf, v102
	v_fmac_f32_e32 v107, 0x3f317217, v102
	v_mov_b32_e32 v102, v107
	v_sub_f32_e32 v102, v106, v102
	v_min_f32_e32 v106, 0, v98
	v_mul_f32_e64 v98, |v98|, s25
	v_exp_f32_e32 v98, v98
	v_mul_f32_e32 v102, 0x3d800000, v102
	v_add_f32_e32 v98, 1.0, v98
	v_log_f32_e32 v98, v98
	s_nop 0
	v_mul_f32_e32 v107, 0x3f317217, v98
	v_fma_f32 v107, v98, s23, -v107
	v_fmac_f32_e32 v107, 0x3377d1cf, v98
	v_fmac_f32_e32 v107, 0x3f317217, v98
	v_mov_b32_e32 v98, v107
	v_sub_f32_e32 v98, v106, v98
	v_mul_f32_e32 v106, 0x3d800000, v98
	v_min_f32_e32 v98, 0, v103
	v_mul_f32_e64 v103, |v103|, s25
	v_exp_f32_e32 v103, v103
	s_nop 0
	v_add_f32_e32 v103, 1.0, v103
	v_log_f32_e32 v103, v103
	s_nop 0
	v_mul_f32_e32 v107, 0x3f317217, v103
	v_fma_f32 v107, v103, s23, -v107
	v_fmac_f32_e32 v107, 0x3377d1cf, v103
	v_fmac_f32_e32 v107, 0x3f317217, v103
	v_mov_b32_e32 v103, v107
	v_sub_f32_e32 v98, v98, v103
	v_min_f32_e32 v103, 0, v99
	v_mul_f32_e64 v99, |v99|, s25
	v_exp_f32_e32 v99, v99
	v_mul_f32_e32 v98, 0x3d800000, v98
	v_cvt_pk_bf16_f32 v97, v102, v98
	v_cvt_pk_bf16_f32 v98, v100, v101
	v_add_f32_e32 v99, 1.0, v99
	v_log_f32_e32 v99, v99
	s_nop 0
	v_mul_f32_e32 v107, 0x3f317217, v99
	v_fma_f32 v107, v99, s23, -v107
	v_fmac_f32_e32 v107, 0x3377d1cf, v99
	v_fmac_f32_e32 v107, 0x3f317217, v99
	v_mov_b32_e32 v99, v107
	v_sub_f32_e32 v99, v103, v99
	v_mul_f32_e32 v99, 0x3d800000, v99
	v_cvt_pk_bf16_f32 v99, v106, v99
	global_store_dwordx4 v[104:105], v[96:99], off offset:256
	global_load_dwordx4 v[98:101], v[128:129], off offset:16
	s_nop 0
	global_load_dwordx4 v[102:105], v[128:129], off
	v_or_b32_e32 v96, 32, v170
	v_ashrrev_i32_e32 v97, 31, v96
	v_lshlrev_b64 v[96:97], 10, v[96:97]
	v_lshl_add_u64 v[96:97], s[58:59], 0, v[96:97]
	s_waitcnt vmcnt(1)
; __device__ __forceinline__ unsigned cvt_pk_bf16(float lo, float hi) { unsigned r; asm volatile("v_cvt_pk_bf16_f32 %0, %1, %2" : "=v"(r) : "v"(lo), "v"(hi)); return r; }
;     __device__ __forceinline__ void operator()(const AccT& acc, const pg8::Unit& u, int wr, int wc, int fr, int fq) const {
;     ...
;             for (int ai = 0; ai < 2; ++ai)
; #pragma unroll
;                 for (int m = 0; m < 4; ++m) {
;                     const int row = row0 + ai * 128 + m * 16; const float rs = rsv[ai * 4 + m];
; #pragma unroll
;                     for (int bj = 0; bj < 2; ++bj) {
;                         const int cg = coff + ct + bj * 128;
;                         const f32x4 b0 = *(const f32x4*)(blr_b + cg), b1 = *(const f32x4*)(blr_b + cg + 4);
;                         f32x4 x0 = acc[ai][bj][m][0] * rs + b0, x1 = acc[ai][bj][m][1] * rs + b1;
; #pragma unroll
;                         for (int j = 0; j < 4; ++j) { x0[j] = (fminf(x0[j], 0.f) - __logf(1.f + __expf(-fabsf(x0[j])))) * (1.f / 16.f); x1[j] = (fminf(x1[j], 0.f) - __logf(1.f + __expf(-fabsf(x1[j])))) * (1.f / 16.f); }
;                         u32x4 w; w.x = cvt_pk_bf16(x0[0], x0[1]); w.y = cvt_pk_bf16(x0[2], x0[3]); w.z = cvt_pk_bf16(x1[0], x1[1]); w.w = cvt_pk_bf16(x1[2], x1[3]);
;                         *(u32x4*)(base + (size_t)row * 512 + cg) = w;
	v_pk_fma_f32 v[98:99], v[88:89], v[172:173], v[98:99] op_sel_hi:[1,0,1]
	s_waitcnt vmcnt(0)
	v_pk_fma_f32 v[92:93], v[92:93], v[172:173], v[102:103] op_sel_hi:[1,0,1]
	v_pk_fma_f32 v[94:95], v[94:95], v[172:173], v[104:105] op_sel_hi:[1,0,1]
	v_mul_f32_e64 v89, |v92|, s25
	v_exp_f32_e32 v89, v89
	v_min_f32_e32 v88, 0, v92
	v_pk_fma_f32 v[90:91], v[90:91], v[172:173], v[100:101] op_sel_hi:[1,0,1]
	v_add_f32_e32 v89, 1.0, v89
	v_log_f32_e32 v89, v89
	s_nop 0
	v_mul_f32_e32 v92, 0x3f317217, v89
	v_fma_f32 v92, v89, s23, -v92
	v_fmac_f32_e32 v92, 0x3377d1cf, v89
	v_fmac_f32_e32 v92, 0x3f317217, v89
	v_mov_b32_e32 v89, v92
	v_mul_f32_e64 v92, |v98|, s25
	v_exp_f32_e32 v92, v92
	v_sub_f32_e32 v88, v88, v89
	v_min_f32_e32 v89, 0, v98
	v_mul_f32_e32 v88, 0x3d800000, v88
	v_add_f32_e32 v92, 1.0, v92
	v_log_f32_e32 v92, v92
	s_nop 0
	v_mul_f32_e32 v98, 0x3f317217, v92
	v_fma_f32 v98, v92, s23, -v98
	v_fmac_f32_e32 v98, 0x3377d1cf, v92
	v_fmac_f32_e32 v98, 0x3f317217, v92
	v_mov_b32_e32 v92, v98
	v_sub_f32_e32 v89, v89, v92
	v_min_f32_e32 v92, 0, v93
	v_mul_f32_e64 v93, |v93|, s25
	v_exp_f32_e32 v93, v93
	v_mul_f32_e32 v89, 0x3d800000, v89
	v_add_f32_e32 v93, 1.0, v93
	v_log_f32_e32 v93, v93
	s_nop 0
	v_mul_f32_e32 v98, 0x3f317217, v93
	v_fma_f32 v98, v93, s23, -v98
	v_fmac_f32_e32 v98, 0x3377d1cf, v93
	v_fmac_f32_e32 v98, 0x3f317217, v93
	v_mov_b32_e32 v93, v98
	v_mul_f32_e64 v98, |v99|, s25
	v_exp_f32_e32 v98, v98
	v_sub_f32_e32 v92, v92, v93
	v_min_f32_e32 v93, 0, v99
	v_mul_f32_e32 v92, 0x3d800000, v92
	v_add_f32_e32 v98, 1.0, v98
	v_log_f32_e32 v98, v98
	s_nop 0
	v_mul_f32_e32 v99, 0x3f317217, v98
	v_fma_f32 v99, v98, s23, -v99
	v_fmac_f32_e32 v99, 0x3377d1cf, v98
	v_fmac_f32_e32 v99, 0x3f317217, v98
	v_mov_b32_e32 v98, v99
	v_sub_f32_e32 v93, v93, v98
	v_min_f32_e32 v98, 0, v94
	v_mul_f32_e64 v94, |v94|, s25
	v_exp_f32_e32 v94, v94
	v_mul_f32_e32 v93, 0x3d800000, v93
	v_add_f32_e32 v94, 1.0, v94
	v_log_f32_e32 v94, v94
	s_nop 0
	v_mul_f32_e32 v99, 0x3f317217, v94
	v_fma_f32 v99, v94, s23, -v99
	v_fmac_f32_e32 v99, 0x3377d1cf, v94
	v_fmac_f32_e32 v99, 0x3f317217, v94
	v_mov_b32_e32 v94, v99
	v_sub_f32_e32 v94, v98, v94
	v_min_f32_e32 v98, 0, v90
	v_mul_f32_e64 v90, |v90|, s25
	v_exp_f32_e32 v90, v90
	v_mul_f32_e32 v94, 0x3d800000, v94
	v_add_f32_e32 v90, 1.0, v90
	v_log_f32_e32 v90, v90
	s_nop 0
	v_mul_f32_e32 v99, 0x3f317217, v90
	v_fma_f32 v99, v90, s23, -v99
	v_fmac_f32_e32 v99, 0x3377d1cf, v90
	v_fmac_f32_e32 v99, 0x3f317217, v90
	v_mov_b32_e32 v90, v99
	v_sub_f32_e32 v90, v98, v90
	v_mul_f32_e32 v98, 0x3d800000, v90
	v_min_f32_e32 v90, 0, v95
	v_mul_f32_e64 v95, |v95|, s25
	v_exp_f32_e32 v95, v95
	s_nop 0
	v_add_f32_e32 v95, 1.0, v95
	v_log_f32_e32 v95, v95
	s_nop 0
	v_mul_f32_e32 v99, 0x3f317217, v95
	v_fma_f32 v99, v95, s23, -v99
	v_fmac_f32_e32 v99, 0x3377d1cf, v95
	v_fmac_f32_e32 v99, 0x3f317217, v95
	v_mov_b32_e32 v95, v99
	v_sub_f32_e32 v90, v90, v95
	v_mul_f32_e32 v95, 0x3d800000, v90
	v_min_f32_e32 v90, 0, v91
	v_mul_f32_e64 v91, |v91|, s25
	v_exp_f32_e32 v91, v91
	s_nop 0
	v_add_f32_e32 v91, 1.0, v91
	v_log_f32_e32 v91, v91
	s_nop 0
	v_mul_f32_e32 v99, 0x3f317217, v91
	v_fma_f32 v99, v91, s23, -v99
	v_fmac_f32_e32 v99, 0x3377d1cf, v91
	v_fmac_f32_e32 v99, 0x3f317217, v91
	v_mov_b32_e32 v91, v99
	v_sub_f32_e32 v90, v90, v91
	v_mul_f32_e32 v99, 0x3d800000, v90
	v_cvt_pk_bf16_f32 v90, v88, v92
	v_cvt_pk_bf16_f32 v91, v94, v95
	v_cvt_pk_bf16_f32 v92, v89, v93
	v_lshl_add_u64 v[88:89], v[96:97], 0, v[122:123]
	v_cvt_pk_bf16_f32 v93, v98, v99
	global_store_dwordx4 v[88:89], v[90:93], off
	global_load_dwordx4 v[90:93], v[128:129], off offset:528
	s_nop 0
	global_load_dwordx4 v[94:97], v[128:129], off offset:512
	s_waitcnt vmcnt(1)
	v_pk_fma_f32 v[90:91], v[80:81], v[172:173], v[90:91] op_sel_hi:[1,0,1]
	s_waitcnt vmcnt(0)
	v_pk_fma_f32 v[84:85], v[84:85], v[172:173], v[94:95] op_sel_hi:[1,0,1]
	v_pk_fma_f32 v[86:87], v[86:87], v[172:173], v[96:97] op_sel_hi:[1,0,1]
	v_mul_f32_e64 v81, |v84|, s25
	v_exp_f32_e32 v81, v81
	v_min_f32_e32 v80, 0, v84
	v_pk_fma_f32 v[82:83], v[82:83], v[172:173], v[92:93] op_sel_hi:[1,0,1]
	v_add_f32_e32 v81, 1.0, v81
	v_log_f32_e32 v81, v81
	s_nop 0
	v_mul_f32_e32 v84, 0x3f317217, v81
	v_fma_f32 v84, v81, s23, -v84
	v_fmac_f32_e32 v84, 0x3377d1cf, v81
	v_fmac_f32_e32 v84, 0x3f317217, v81
	v_mov_b32_e32 v81, v84
	v_mul_f32_e64 v84, |v90|, s25
	v_exp_f32_e32 v84, v84
	v_sub_f32_e32 v80, v80, v81
	v_min_f32_e32 v81, 0, v90
	v_mul_f32_e32 v80, 0x3d800000, v80
	v_add_f32_e32 v84, 1.0, v84
	v_log_f32_e32 v84, v84
	s_nop 0
	v_mul_f32_e32 v90, 0x3f317217, v84
	v_fma_f32 v90, v84, s23, -v90
	v_fmac_f32_e32 v90, 0x3377d1cf, v84
	v_fmac_f32_e32 v90, 0x3f317217, v84
	v_mov_b32_e32 v84, v90
	v_sub_f32_e32 v81, v81, v84
	v_mul_f32_e32 v84, 0x3d800000, v81
	v_min_f32_e32 v81, 0, v85
	v_mul_f32_e64 v85, |v85|, s25
	v_exp_f32_e32 v85, v85
	s_nop 0
	v_add_f32_e32 v85, 1.0, v85
	v_log_f32_e32 v85, v85
	s_nop 0
	v_mul_f32_e32 v90, 0x3f317217, v85
	v_fma_f32 v90, v85, s23, -v90
	v_fmac_f32_e32 v90, 0x3377d1cf, v85
	v_fmac_f32_e32 v90, 0x3f317217, v85
	v_mov_b32_e32 v85, v90
	v_mul_f32_e64 v90, |v91|, s25
	v_exp_f32_e32 v90, v90
	v_sub_f32_e32 v81, v81, v85
	v_min_f32_e32 v85, 0, v91
	v_mul_f32_e32 v81, 0x3d800000, v81
	v_add_f32_e32 v90, 1.0, v90
	v_cvt_pk_bf16_f32 v80, v80, v81
	v_log_f32_e32 v90, v90
	s_nop 0
	v_mul_f32_e32 v91, 0x3f317217, v90
	v_fma_f32 v91, v90, s23, -v91
	v_fmac_f32_e32 v91, 0x3377d1cf, v90
	v_fmac_f32_e32 v91, 0x3f317217, v90
	v_mov_b32_e32 v90, v91
	v_sub_f32_e32 v85, v85, v90
	v_min_f32_e32 v90, 0, v86
	v_mul_f32_e64 v86, |v86|, s25
	v_exp_f32_e32 v86, v86
	v_mul_f32_e32 v85, 0x3d800000, v85
; __device__ __forceinline__ unsigned cvt_pk_bf16(float lo, float hi) { unsigned r; asm volatile("v_cvt_pk_bf16_f32 %0, %1, %2" : "=v"(r) : "v"(lo), "v"(hi)); return r; }
;     __device__ __forceinline__ void operator()(const AccT& acc, const pg8::Unit& u, int wr, int wc, int fr, int fq) const {
;     ...
;             for (int ai = 0; ai < 2; ++ai)
; #pragma unroll
;                 for (int m = 0; m < 4; ++m) {
;                     const int row = row0 + ai * 128 + m * 16; const float rs = rsv[ai * 4 + m];
; #pragma unroll
;                     for (int bj = 0; bj < 2; ++bj) {
;                         const int cg = coff + ct + bj * 128;
;                         const f32x4 b0 = *(const f32x4*)(blr_b + cg), b1 = *(const f32x4*)(blr_b + cg + 4);
;                         f32x4 x0 = acc[ai][bj][m][0] * rs + b0, x1 = acc[ai][bj][m][1] * rs + b1;
; #pragma unroll
;                         for (int j = 0; j < 4; ++j) { x0[j] = (fminf(x0[j], 0.f) - __logf(1.f + __expf(-fabsf(x0[j])))) * (1.f / 16.f); x1[j] = (fminf(x1[j], 0.f) - __logf(1.f + __expf(-fabsf(x1[j])))) * (1.f / 16.f); }
;                         u32x4 w; w.x = cvt_pk_bf16(x0[0], x0[1]); w.y = cvt_pk_bf16(x0[2], x0[3]); w.z = cvt_pk_bf16(x1[0], x1[1]); w.w = cvt_pk_bf16(x1[2], x1[3]);
;                         *(u32x4*)(base + (size_t)row * 512 + cg) = w;
	v_add_f32_e32 v86, 1.0, v86
	v_log_f32_e32 v86, v86
	s_nop 0
	v_mul_f32_e32 v91, 0x3f317217, v86
	v_fma_f32 v91, v86, s23, -v91
	v_fmac_f32_e32 v91, 0x3377d1cf, v86
	v_fmac_f32_e32 v91, 0x3f317217, v86
	v_mov_b32_e32 v86, v91
	v_sub_f32_e32 v86, v90, v86
	v_min_f32_e32 v90, 0, v82
	v_mul_f32_e64 v82, |v82|, s25
	v_exp_f32_e32 v82, v82
	v_mul_f32_e32 v86, 0x3d800000, v86
	v_add_f32_e32 v82, 1.0, v82
	v_log_f32_e32 v82, v82
	s_nop 0
	v_mul_f32_e32 v91, 0x3f317217, v82
	v_fma_f32 v91, v82, s23, -v91
	v_fmac_f32_e32 v91, 0x3377d1cf, v82
	v_fmac_f32_e32 v91, 0x3f317217, v82
	v_mov_b32_e32 v82, v91
	v_sub_f32_e32 v82, v90, v82
	v_mul_f32_e32 v90, 0x3d800000, v82
	v_min_f32_e32 v82, 0, v87
	v_mul_f32_e64 v87, |v87|, s25
	v_exp_f32_e32 v87, v87
	s_nop 0
	v_add_f32_e32 v87, 1.0, v87
	v_log_f32_e32 v87, v87
	s_nop 0
	v_mul_f32_e32 v91, 0x3f317217, v87
	v_fma_f32 v91, v87, s23, -v91
	v_fmac_f32_e32 v91, 0x3377d1cf, v87
	v_fmac_f32_e32 v91, 0x3f317217, v87
	v_mov_b32_e32 v87, v91
	v_sub_f32_e32 v82, v82, v87
	v_min_f32_e32 v87, 0, v83
	v_mul_f32_e64 v83, |v83|, s25
	v_exp_f32_e32 v83, v83
	v_mul_f32_e32 v82, 0x3d800000, v82
	v_cvt_pk_bf16_f32 v81, v86, v82
	v_cvt_pk_bf16_f32 v82, v84, v85
	v_add_f32_e32 v83, 1.0, v83
	v_log_f32_e32 v83, v83
	s_nop 0
	v_mul_f32_e32 v91, 0x3f317217, v83
	v_fma_f32 v91, v83, s23, -v91
	v_fmac_f32_e32 v91, 0x3377d1cf, v83
	v_fmac_f32_e32 v91, 0x3f317217, v83
	v_mov_b32_e32 v83, v91
	v_sub_f32_e32 v83, v87, v83
	v_mul_f32_e32 v83, 0x3d800000, v83
	v_cvt_pk_bf16_f32 v83, v90, v83
	global_store_dwordx4 v[88:89], v[80:83], off offset:256
	global_load_dwordx4 v[82:85], v[128:129], off offset:16
	s_nop 0
	global_load_dwordx4 v[86:89], v[128:129], off
	v_or_b32_e32 v80, 48, v170
	v_ashrrev_i32_e32 v81, 31, v80
	v_lshlrev_b64 v[80:81], 10, v[80:81]
	v_lshl_add_u64 v[80:81], s[58:59], 0, v[80:81]
	s_waitcnt vmcnt(1)
	v_pk_fma_f32 v[82:83], v[72:73], v[168:169], v[82:83] op_sel_hi:[1,0,1]
	s_waitcnt vmcnt(0)
	v_pk_fma_f32 v[76:77], v[76:77], v[168:169], v[86:87] op_sel_hi:[1,0,1]
	v_pk_fma_f32 v[78:79], v[78:79], v[168:169], v[88:89] op_sel_hi:[1,0,1]
	v_mul_f32_e64 v73, |v76|, s25
	v_exp_f32_e32 v73, v73
	v_min_f32_e32 v72, 0, v76
	v_pk_fma_f32 v[74:75], v[74:75], v[168:169], v[84:85] op_sel_hi:[1,0,1]
	v_add_f32_e32 v73, 1.0, v73
	v_log_f32_e32 v73, v73
	s_nop 0
	v_mul_f32_e32 v76, 0x3f317217, v73
	v_fma_f32 v76, v73, s23, -v76
	v_fmac_f32_e32 v76, 0x3377d1cf, v73
	v_fmac_f32_e32 v76, 0x3f317217, v73
	v_mov_b32_e32 v73, v76
	v_mul_f32_e64 v76, |v82|, s25
	v_exp_f32_e32 v76, v76
	v_sub_f32_e32 v72, v72, v73
	v_min_f32_e32 v73, 0, v82
	v_mul_f32_e32 v72, 0x3d800000, v72
	v_add_f32_e32 v76, 1.0, v76
	v_log_f32_e32 v76, v76
	s_nop 0
	v_mul_f32_e32 v82, 0x3f317217, v76
	v_fma_f32 v82, v76, s23, -v82
	v_fmac_f32_e32 v82, 0x3377d1cf, v76
	v_fmac_f32_e32 v82, 0x3f317217, v76
	v_mov_b32_e32 v76, v82
	v_sub_f32_e32 v73, v73, v76
	v_min_f32_e32 v76, 0, v77
	v_mul_f32_e64 v77, |v77|, s25
	v_exp_f32_e32 v77, v77
	v_mul_f32_e32 v73, 0x3d800000, v73
	v_add_f32_e32 v77, 1.0, v77
	v_log_f32_e32 v77, v77
	s_nop 0
	v_mul_f32_e32 v82, 0x3f317217, v77
	v_fma_f32 v82, v77, s23, -v82
	v_fmac_f32_e32 v82, 0x3377d1cf, v77
	v_fmac_f32_e32 v82, 0x3f317217, v77
	v_mov_b32_e32 v77, v82
	v_mul_f32_e64 v82, |v83|, s25
	v_exp_f32_e32 v82, v82
	v_sub_f32_e32 v76, v76, v77
	v_min_f32_e32 v77, 0, v83
	v_mul_f32_e32 v76, 0x3d800000, v76
	v_add_f32_e32 v82, 1.0, v82
	v_log_f32_e32 v82, v82
	s_nop 0
	v_mul_f32_e32 v83, 0x3f317217, v82
	v_fma_f32 v83, v82, s23, -v83
	v_fmac_f32_e32 v83, 0x3377d1cf, v82
	v_fmac_f32_e32 v83, 0x3f317217, v82
	v_mov_b32_e32 v82, v83
	v_sub_f32_e32 v77, v77, v82
	v_min_f32_e32 v82, 0, v78
	v_mul_f32_e64 v78, |v78|, s25
	v_exp_f32_e32 v78, v78
	v_mul_f32_e32 v77, 0x3d800000, v77
	v_add_f32_e32 v78, 1.0, v78
	v_log_f32_e32 v78, v78
	s_nop 0
	v_mul_f32_e32 v83, 0x3f317217, v78
	v_fma_f32 v83, v78, s23, -v83
	v_fmac_f32_e32 v83, 0x3377d1cf, v78
	v_fmac_f32_e32 v83, 0x3f317217, v78
	v_mov_b32_e32 v78, v83
	v_sub_f32_e32 v78, v82, v78
	v_min_f32_e32 v82, 0, v74
	v_mul_f32_e64 v74, |v74|, s25
	v_exp_f32_e32 v74, v74
	v_mul_f32_e32 v78, 0x3d800000, v78
	v_add_f32_e32 v74, 1.0, v74
	v_log_f32_e32 v74, v74
	s_nop 0
	v_mul_f32_e32 v83, 0x3f317217, v74
	v_fma_f32 v83, v74, s23, -v83
	v_fmac_f32_e32 v83, 0x3377d1cf, v74
	v_fmac_f32_e32 v83, 0x3f317217, v74
	v_mov_b32_e32 v74, v83
	v_sub_f32_e32 v74, v82, v74
	v_mul_f32_e32 v82, 0x3d800000, v74
	v_min_f32_e32 v74, 0, v79
	v_mul_f32_e64 v79, |v79|, s25
	v_exp_f32_e32 v79, v79
	s_nop 0
	v_add_f32_e32 v79, 1.0, v79
	v_log_f32_e32 v79, v79
	s_nop 0
	v_mul_f32_e32 v83, 0x3f317217, v79
	v_fma_f32 v83, v79, s23, -v83
	v_fmac_f32_e32 v83, 0x3377d1cf, v79
	v_fmac_f32_e32 v83, 0x3f317217, v79
	v_mov_b32_e32 v79, v83
	v_sub_f32_e32 v74, v74, v79
	v_mul_f32_e32 v79, 0x3d800000, v74
	v_min_f32_e32 v74, 0, v75
	v_mul_f32_e64 v75, |v75|, s25
	v_exp_f32_e32 v75, v75
	s_nop 0
	v_add_f32_e32 v75, 1.0, v75
	v_log_f32_e32 v75, v75
	s_nop 0
	v_mul_f32_e32 v83, 0x3f317217, v75
	v_fma_f32 v83, v75, s23, -v83
	v_fmac_f32_e32 v83, 0x3377d1cf, v75
	v_fmac_f32_e32 v83, 0x3f317217, v75
	v_mov_b32_e32 v75, v83
	v_sub_f32_e32 v74, v74, v75
	v_mul_f32_e32 v83, 0x3d800000, v74
	v_cvt_pk_bf16_f32 v74, v72, v76
	v_cvt_pk_bf16_f32 v75, v78, v79
	v_cvt_pk_bf16_f32 v76, v73, v77
	v_lshl_add_u64 v[72:73], v[80:81], 0, v[122:123]
	v_cvt_pk_bf16_f32 v77, v82, v83
	global_store_dwordx4 v[72:73], v[74:77], off
	global_load_dwordx4 v[74:77], v[128:129], off offset:528
	s_nop 0
	global_load_dwordx4 v[78:81], v[128:129], off offset:512
	s_waitcnt vmcnt(1)
	v_pk_fma_f32 v[74:75], v[64:65], v[168:169], v[74:75] op_sel_hi:[1,0,1]
	s_waitcnt vmcnt(0)
; __device__ __forceinline__ unsigned cvt_pk_bf16(float lo, float hi) { unsigned r; asm volatile("v_cvt_pk_bf16_f32 %0, %1, %2" : "=v"(r) : "v"(lo), "v"(hi)); return r; }
;     __device__ __forceinline__ void operator()(const AccT& acc, const pg8::Unit& u, int wr, int wc, int fr, int fq) const {
;     ...
;             for (int ai = 0; ai < 2; ++ai)
; #pragma unroll
;                 for (int m = 0; m < 4; ++m) {
;                     const int row = row0 + ai * 128 + m * 16; const float rs = rsv[ai * 4 + m];
; #pragma unroll
;                     for (int bj = 0; bj < 2; ++bj) {
;                         const int cg = coff + ct + bj * 128;
;                         const f32x4 b0 = *(const f32x4*)(blr_b + cg), b1 = *(const f32x4*)(blr_b + cg + 4);
;                         f32x4 x0 = acc[ai][bj][m][0] * rs + b0, x1 = acc[ai][bj][m][1] * rs + b1;
; #pragma unroll
;                         for (int j = 0; j < 4; ++j) { x0[j] = (fminf(x0[j], 0.f) - __logf(1.f + __expf(-fabsf(x0[j])))) * (1.f / 16.f); x1[j] = (fminf(x1[j], 0.f) - __logf(1.f + __expf(-fabsf(x1[j])))) * (1.f / 16.f); }
;                         u32x4 w; w.x = cvt_pk_bf16(x0[0], x0[1]); w.y = cvt_pk_bf16(x0[2], x0[3]); w.z = cvt_pk_bf16(x1[0], x1[1]); w.w = cvt_pk_bf16(x1[2], x1[3]);
;                         *(u32x4*)(base + (size_t)row * 512 + cg) = w;
	v_pk_fma_f32 v[68:69], v[68:69], v[168:169], v[78:79] op_sel_hi:[1,0,1]
	v_pk_fma_f32 v[70:71], v[70:71], v[168:169], v[80:81] op_sel_hi:[1,0,1]
	v_mul_f32_e64 v65, |v68|, s25
	v_exp_f32_e32 v65, v65
	v_min_f32_e32 v64, 0, v68
	v_pk_fma_f32 v[66:67], v[66:67], v[168:169], v[76:77] op_sel_hi:[1,0,1]
	v_add_f32_e32 v65, 1.0, v65
	v_log_f32_e32 v65, v65
	s_nop 0
	v_mul_f32_e32 v68, 0x3f317217, v65
	v_fma_f32 v68, v65, s23, -v68
	v_fmac_f32_e32 v68, 0x3377d1cf, v65
	v_fmac_f32_e32 v68, 0x3f317217, v65
	v_mov_b32_e32 v65, v68
	v_mul_f32_e64 v68, |v74|, s25
	v_exp_f32_e32 v68, v68
	v_sub_f32_e32 v64, v64, v65
	v_min_f32_e32 v65, 0, v74
	v_mul_f32_e32 v64, 0x3d800000, v64
	v_add_f32_e32 v68, 1.0, v68
	v_log_f32_e32 v68, v68
	s_nop 0
	v_mul_f32_e32 v74, 0x3f317217, v68
	v_fma_f32 v74, v68, s23, -v74
	v_fmac_f32_e32 v74, 0x3377d1cf, v68
	v_fmac_f32_e32 v74, 0x3f317217, v68
	v_mov_b32_e32 v68, v74
	v_sub_f32_e32 v65, v65, v68
	v_mul_f32_e32 v68, 0x3d800000, v65
	v_min_f32_e32 v65, 0, v69
	v_mul_f32_e64 v69, |v69|, s25
	v_exp_f32_e32 v69, v69
	s_nop 0
	v_add_f32_e32 v69, 1.0, v69
	v_log_f32_e32 v69, v69
	s_nop 0
	v_mul_f32_e32 v74, 0x3f317217, v69
	v_fma_f32 v74, v69, s23, -v74
	v_fmac_f32_e32 v74, 0x3377d1cf, v69
	v_fmac_f32_e32 v74, 0x3f317217, v69
	v_mov_b32_e32 v69, v74
	v_mul_f32_e64 v74, |v75|, s25
	v_exp_f32_e32 v74, v74
	v_sub_f32_e32 v65, v65, v69
	v_min_f32_e32 v69, 0, v75
	v_mul_f32_e32 v65, 0x3d800000, v65
	v_add_f32_e32 v74, 1.0, v74
	v_cvt_pk_bf16_f32 v64, v64, v65
	v_log_f32_e32 v74, v74
	s_nop 0
	v_mul_f32_e32 v75, 0x3f317217, v74
	v_fma_f32 v75, v74, s23, -v75
	v_fmac_f32_e32 v75, 0x3377d1cf, v74
	v_fmac_f32_e32 v75, 0x3f317217, v74
	v_mov_b32_e32 v74, v75
	v_sub_f32_e32 v69, v69, v74
	v_min_f32_e32 v74, 0, v70
	v_mul_f32_e64 v70, |v70|, s25
	v_exp_f32_e32 v70, v70
	v_mul_f32_e32 v69, 0x3d800000, v69
	v_add_f32_e32 v70, 1.0, v70
	v_log_f32_e32 v70, v70
	s_nop 0
	v_mul_f32_e32 v75, 0x3f317217, v70
	v_fma_f32 v75, v70, s23, -v75
	v_fmac_f32_e32 v75, 0x3377d1cf, v70
	v_fmac_f32_e32 v75, 0x3f317217, v70
	v_mov_b32_e32 v70, v75
	v_sub_f32_e32 v70, v74, v70
	v_min_f32_e32 v74, 0, v66
	v_mul_f32_e64 v66, |v66|, s25
	v_exp_f32_e32 v66, v66
	v_mul_f32_e32 v70, 0x3d800000, v70
	v_add_f32_e32 v66, 1.0, v66
	v_log_f32_e32 v66, v66
	s_nop 0
	v_mul_f32_e32 v75, 0x3f317217, v66
	v_fma_f32 v75, v66, s23, -v75
	v_fmac_f32_e32 v75, 0x3377d1cf, v66
	v_fmac_f32_e32 v75, 0x3f317217, v66
	v_mov_b32_e32 v66, v75
	v_sub_f32_e32 v66, v74, v66
	v_mul_f32_e32 v74, 0x3d800000, v66
	v_min_f32_e32 v66, 0, v71
	v_mul_f32_e64 v71, |v71|, s25
	v_exp_f32_e32 v71, v71
	s_nop 0
	v_add_f32_e32 v71, 1.0, v71
	v_log_f32_e32 v71, v71
	s_nop 0
	v_mul_f32_e32 v75, 0x3f317217, v71
	v_fma_f32 v75, v71, s23, -v75
	v_fmac_f32_e32 v75, 0x3377d1cf, v71
	v_fmac_f32_e32 v75, 0x3f317217, v71
	v_mov_b32_e32 v71, v75
	v_sub_f32_e32 v66, v66, v71
	v_min_f32_e32 v71, 0, v67
	v_mul_f32_e64 v67, |v67|, s25
	v_exp_f32_e32 v67, v67
	v_mul_f32_e32 v66, 0x3d800000, v66
	v_cvt_pk_bf16_f32 v65, v70, v66
	v_cvt_pk_bf16_f32 v66, v68, v69
	v_add_f32_e32 v67, 1.0, v67
	v_log_f32_e32 v67, v67
	s_nop 0
	v_mul_f32_e32 v75, 0x3f317217, v67
	v_fma_f32 v75, v67, s23, -v75
	v_fmac_f32_e32 v75, 0x3377d1cf, v67
	v_fmac_f32_e32 v75, 0x3f317217, v67
	v_mov_b32_e32 v67, v75
	v_sub_f32_e32 v67, v71, v67
	v_mul_f32_e32 v67, 0x3d800000, v67
	v_cvt_pk_bf16_f32 v67, v74, v67
	global_store_dwordx4 v[72:73], v[64:67], off offset:256
	global_load_dwordx4 v[66:69], v[128:129], off offset:16
	s_nop 0
	global_load_dwordx4 v[70:73], v[128:129], off
	v_lshlrev_b64 v[64:65], 10, v[166:167]
	v_lshl_add_u64 v[64:65], s[58:59], 0, v[64:65]
	s_waitcnt vmcnt(1)
	v_pk_fma_f32 v[66:67], v[56:57], v[164:165], v[66:67] op_sel_hi:[1,0,1]
	s_waitcnt vmcnt(0)
	v_pk_fma_f32 v[60:61], v[60:61], v[164:165], v[70:71] op_sel_hi:[1,0,1]
	v_pk_fma_f32 v[62:63], v[62:63], v[164:165], v[72:73] op_sel_hi:[1,0,1]
	v_mul_f32_e64 v57, |v60|, s25
	v_exp_f32_e32 v57, v57
	v_min_f32_e32 v56, 0, v60
	v_pk_fma_f32 v[58:59], v[58:59], v[164:165], v[68:69] op_sel_hi:[1,0,1]
	v_add_f32_e32 v57, 1.0, v57
	v_log_f32_e32 v57, v57
	s_nop 0
	v_mul_f32_e32 v60, 0x3f317217, v57
	v_fma_f32 v60, v57, s23, -v60
	v_fmac_f32_e32 v60, 0x3377d1cf, v57
	v_fmac_f32_e32 v60, 0x3f317217, v57
	v_mov_b32_e32 v57, v60
	v_mul_f32_e64 v60, |v66|, s25
	v_exp_f32_e32 v60, v60
	v_sub_f32_e32 v56, v56, v57
	v_min_f32_e32 v57, 0, v66
	v_mul_f32_e32 v56, 0x3d800000, v56
	v_add_f32_e32 v60, 1.0, v60
	v_log_f32_e32 v60, v60
	s_nop 0
	v_mul_f32_e32 v66, 0x3f317217, v60
	v_fma_f32 v66, v60, s23, -v66
	v_fmac_f32_e32 v66, 0x3377d1cf, v60
	v_fmac_f32_e32 v66, 0x3f317217, v60
	v_mov_b32_e32 v60, v66
	v_sub_f32_e32 v57, v57, v60
	v_min_f32_e32 v60, 0, v61
	v_mul_f32_e64 v61, |v61|, s25
	v_exp_f32_e32 v61, v61
	v_mul_f32_e32 v57, 0x3d800000, v57
	v_add_f32_e32 v61, 1.0, v61
	v_log_f32_e32 v61, v61
	s_nop 0
	v_mul_f32_e32 v66, 0x3f317217, v61
	v_fma_f32 v66, v61, s23, -v66
	v_fmac_f32_e32 v66, 0x3377d1cf, v61
	v_fmac_f32_e32 v66, 0x3f317217, v61
	v_mov_b32_e32 v61, v66
	v_mul_f32_e64 v66, |v67|, s25
	v_exp_f32_e32 v66, v66
	v_sub_f32_e32 v60, v60, v61
	v_min_f32_e32 v61, 0, v67
	v_mul_f32_e32 v60, 0x3d800000, v60
	v_add_f32_e32 v66, 1.0, v66
	v_log_f32_e32 v66, v66
	s_nop 0
	v_mul_f32_e32 v67, 0x3f317217, v66
	v_fma_f32 v67, v66, s23, -v67
	v_fmac_f32_e32 v67, 0x3377d1cf, v66
	v_fmac_f32_e32 v67, 0x3f317217, v66
	v_mov_b32_e32 v66, v67
	v_sub_f32_e32 v61, v61, v66
	v_min_f32_e32 v66, 0, v62
	v_mul_f32_e64 v62, |v62|, s25
	v_exp_f32_e32 v62, v62
	v_mul_f32_e32 v61, 0x3d800000, v61
	v_add_f32_e32 v62, 1.0, v62
	v_log_f32_e32 v62, v62
	s_nop 0
	v_mul_f32_e32 v67, 0x3f317217, v62
; __device__ __forceinline__ unsigned cvt_pk_bf16(float lo, float hi) { unsigned r; asm volatile("v_cvt_pk_bf16_f32 %0, %1, %2" : "=v"(r) : "v"(lo), "v"(hi)); return r; }
;     __device__ __forceinline__ void operator()(const AccT& acc, const pg8::Unit& u, int wr, int wc, int fr, int fq) const {
;     ...
;             for (int ai = 0; ai < 2; ++ai)
; #pragma unroll
;                 for (int m = 0; m < 4; ++m) {
;                     const int row = row0 + ai * 128 + m * 16; const float rs = rsv[ai * 4 + m];
; #pragma unroll
;                     for (int bj = 0; bj < 2; ++bj) {
;                         const int cg = coff + ct + bj * 128;
;                         const f32x4 b0 = *(const f32x4*)(blr_b + cg), b1 = *(const f32x4*)(blr_b + cg + 4);
;                         f32x4 x0 = acc[ai][bj][m][0] * rs + b0, x1 = acc[ai][bj][m][1] * rs + b1;
; #pragma unroll
;                         for (int j = 0; j < 4; ++j) { x0[j] = (fminf(x0[j], 0.f) - __logf(1.f + __expf(-fabsf(x0[j])))) * (1.f / 16.f); x1[j] = (fminf(x1[j], 0.f) - __logf(1.f + __expf(-fabsf(x1[j])))) * (1.f / 16.f); }
;                         u32x4 w; w.x = cvt_pk_bf16(x0[0], x0[1]); w.y = cvt_pk_bf16(x0[2], x0[3]); w.z = cvt_pk_bf16(x1[0], x1[1]); w.w = cvt_pk_bf16(x1[2], x1[3]);
;                         *(u32x4*)(base + (size_t)row * 512 + cg) = w;
	v_fma_f32 v67, v62, s23, -v67
	v_fmac_f32_e32 v67, 0x3377d1cf, v62
	v_fmac_f32_e32 v67, 0x3f317217, v62
	v_mov_b32_e32 v62, v67
	v_sub_f32_e32 v62, v66, v62
	v_min_f32_e32 v66, 0, v58
	v_mul_f32_e64 v58, |v58|, s25
	v_exp_f32_e32 v58, v58
	v_mul_f32_e32 v62, 0x3d800000, v62
	v_add_f32_e32 v58, 1.0, v58
	v_log_f32_e32 v58, v58
	s_nop 0
	v_mul_f32_e32 v67, 0x3f317217, v58
	v_fma_f32 v67, v58, s23, -v67
	v_fmac_f32_e32 v67, 0x3377d1cf, v58
	v_fmac_f32_e32 v67, 0x3f317217, v58
	v_mov_b32_e32 v58, v67
	v_sub_f32_e32 v58, v66, v58
	v_mul_f32_e32 v66, 0x3d800000, v58
	v_min_f32_e32 v58, 0, v63
	v_mul_f32_e64 v63, |v63|, s25
	v_exp_f32_e32 v63, v63
	s_nop 0
	v_add_f32_e32 v63, 1.0, v63
	v_log_f32_e32 v63, v63
	s_nop 0
	v_mul_f32_e32 v67, 0x3f317217, v63
	v_fma_f32 v67, v63, s23, -v67
	v_fmac_f32_e32 v67, 0x3377d1cf, v63
	v_fmac_f32_e32 v67, 0x3f317217, v63
	v_mov_b32_e32 v63, v67
	v_sub_f32_e32 v58, v58, v63
	v_mul_f32_e32 v63, 0x3d800000, v58
	v_min_f32_e32 v58, 0, v59
	v_mul_f32_e64 v59, |v59|, s25
	v_exp_f32_e32 v59, v59
	s_nop 0
	v_add_f32_e32 v59, 1.0, v59
	v_log_f32_e32 v59, v59
	s_nop 0
	v_mul_f32_e32 v67, 0x3f317217, v59
	v_fma_f32 v67, v59, s23, -v67
	v_fmac_f32_e32 v67, 0x3377d1cf, v59
	v_fmac_f32_e32 v67, 0x3f317217, v59
	v_mov_b32_e32 v59, v67
	v_sub_f32_e32 v58, v58, v59
	v_mul_f32_e32 v67, 0x3d800000, v58
	v_cvt_pk_bf16_f32 v58, v56, v60
	v_cvt_pk_bf16_f32 v59, v62, v63
	v_cvt_pk_bf16_f32 v60, v57, v61
	v_lshl_add_u64 v[56:57], v[64:65], 0, v[122:123]
	v_cvt_pk_bf16_f32 v61, v66, v67
	global_store_dwordx4 v[56:57], v[58:61], off
	global_load_dwordx4 v[58:61], v[128:129], off offset:528
	s_nop 0
	global_load_dwordx4 v[62:65], v[128:129], off offset:512
	s_waitcnt vmcnt(1)
	v_pk_fma_f32 v[58:59], v[48:49], v[164:165], v[58:59] op_sel_hi:[1,0,1]
	s_waitcnt vmcnt(0)
	v_pk_fma_f32 v[52:53], v[52:53], v[164:165], v[62:63] op_sel_hi:[1,0,1]
	v_pk_fma_f32 v[54:55], v[54:55], v[164:165], v[64:65] op_sel_hi:[1,0,1]
	v_mul_f32_e64 v49, |v52|, s25
	v_exp_f32_e32 v49, v49
	v_min_f32_e32 v48, 0, v52
	v_pk_fma_f32 v[50:51], v[50:51], v[164:165], v[60:61] op_sel_hi:[1,0,1]
	v_add_f32_e32 v49, 1.0, v49
	v_log_f32_e32 v49, v49
	s_nop 0
	v_mul_f32_e32 v52, 0x3f317217, v49
	v_fma_f32 v52, v49, s23, -v52
	v_fmac_f32_e32 v52, 0x3377d1cf, v49
	v_fmac_f32_e32 v52, 0x3f317217, v49
	v_mov_b32_e32 v49, v52
	v_mul_f32_e64 v52, |v58|, s25
	v_exp_f32_e32 v52, v52
	v_sub_f32_e32 v48, v48, v49
	v_min_f32_e32 v49, 0, v58
	v_mul_f32_e32 v48, 0x3d800000, v48
	v_add_f32_e32 v52, 1.0, v52
	v_log_f32_e32 v52, v52
	s_nop 0
	v_mul_f32_e32 v58, 0x3f317217, v52
	v_fma_f32 v58, v52, s23, -v58
	v_fmac_f32_e32 v58, 0x3377d1cf, v52
	v_fmac_f32_e32 v58, 0x3f317217, v52
	v_mov_b32_e32 v52, v58
	v_sub_f32_e32 v49, v49, v52
	v_mul_f32_e32 v52, 0x3d800000, v49
	v_min_f32_e32 v49, 0, v53
	v_mul_f32_e64 v53, |v53|, s25
	v_exp_f32_e32 v53, v53
	s_nop 0
	v_add_f32_e32 v53, 1.0, v53
	v_log_f32_e32 v53, v53
	s_nop 0
	v_mul_f32_e32 v58, 0x3f317217, v53
	v_fma_f32 v58, v53, s23, -v58
	v_fmac_f32_e32 v58, 0x3377d1cf, v53
	v_fmac_f32_e32 v58, 0x3f317217, v53
	v_mov_b32_e32 v53, v58
	v_mul_f32_e64 v58, |v59|, s25
	v_exp_f32_e32 v58, v58
	v_sub_f32_e32 v49, v49, v53
	v_min_f32_e32 v53, 0, v59
	v_mul_f32_e32 v49, 0x3d800000, v49
	v_add_f32_e32 v58, 1.0, v58
	v_cvt_pk_bf16_f32 v48, v48, v49
	v_log_f32_e32 v58, v58
	s_nop 0
	v_mul_f32_e32 v59, 0x3f317217, v58
	v_fma_f32 v59, v58, s23, -v59
	v_fmac_f32_e32 v59, 0x3377d1cf, v58
	v_fmac_f32_e32 v59, 0x3f317217, v58
	v_mov_b32_e32 v58, v59
	v_sub_f32_e32 v53, v53, v58
	v_min_f32_e32 v58, 0, v54
	v_mul_f32_e64 v54, |v54|, s25
	v_exp_f32_e32 v54, v54
	v_mul_f32_e32 v53, 0x3d800000, v53
	v_add_f32_e32 v54, 1.0, v54
	v_log_f32_e32 v54, v54
	s_nop 0
	v_mul_f32_e32 v59, 0x3f317217, v54
	v_fma_f32 v59, v54, s23, -v59
	v_fmac_f32_e32 v59, 0x3377d1cf, v54
	v_fmac_f32_e32 v59, 0x3f317217, v54
	v_mov_b32_e32 v54, v59
	v_sub_f32_e32 v54, v58, v54
	v_min_f32_e32 v58, 0, v50
	v_mul_f32_e64 v50, |v50|, s25
	v_exp_f32_e32 v50, v50
	v_mul_f32_e32 v54, 0x3d800000, v54
	v_add_f32_e32 v50, 1.0, v50
	v_log_f32_e32 v50, v50
	s_nop 0
	v_mul_f32_e32 v59, 0x3f317217, v50
	v_fma_f32 v59, v50, s23, -v59
	v_fmac_f32_e32 v59, 0x3377d1cf, v50
	v_fmac_f32_e32 v59, 0x3f317217, v50
	v_mov_b32_e32 v50, v59
	v_sub_f32_e32 v50, v58, v50
	v_mul_f32_e32 v58, 0x3d800000, v50
	v_min_f32_e32 v50, 0, v55
	v_mul_f32_e64 v55, |v55|, s25
	v_exp_f32_e32 v55, v55
	s_nop 0
	v_add_f32_e32 v55, 1.0, v55
	v_log_f32_e32 v55, v55
	s_nop 0
	v_mul_f32_e32 v59, 0x3f317217, v55
	v_fma_f32 v59, v55, s23, -v59
	v_fmac_f32_e32 v59, 0x3377d1cf, v55
	v_fmac_f32_e32 v59, 0x3f317217, v55
	v_mov_b32_e32 v55, v59
	v_sub_f32_e32 v50, v50, v55
	v_min_f32_e32 v55, 0, v51
	v_mul_f32_e64 v51, |v51|, s25
	v_exp_f32_e32 v51, v51
	v_mul_f32_e32 v50, 0x3d800000, v50
	v_cvt_pk_bf16_f32 v49, v54, v50
	v_cvt_pk_bf16_f32 v50, v52, v53
	v_add_f32_e32 v51, 1.0, v51
	v_log_f32_e32 v51, v51
	s_nop 0
	v_mul_f32_e32 v59, 0x3f317217, v51
	v_fma_f32 v59, v51, s23, -v59
	v_fmac_f32_e32 v59, 0x3377d1cf, v51
	v_fmac_f32_e32 v59, 0x3f317217, v51
	v_mov_b32_e32 v51, v59
	v_sub_f32_e32 v51, v55, v51
	v_mul_f32_e32 v51, 0x3d800000, v51
	v_cvt_pk_bf16_f32 v51, v58, v51
	global_store_dwordx4 v[56:57], v[48:51], off offset:256
	global_load_dwordx4 v[48:51], v[128:129], off offset:16
	s_nop 0
	global_load_dwordx4 v[52:55], v[128:129], off
	s_waitcnt vmcnt(1)
	v_pk_fma_f32 v[48:49], v[40:41], v[162:163], v[48:49] op_sel_hi:[1,0,1]
	s_waitcnt vmcnt(0)
; __device__ __forceinline__ unsigned cvt_pk_bf16(float lo, float hi) { unsigned r; asm volatile("v_cvt_pk_bf16_f32 %0, %1, %2" : "=v"(r) : "v"(lo), "v"(hi)); return r; }
;     __device__ __forceinline__ void operator()(const AccT& acc, const pg8::Unit& u, int wr, int wc, int fr, int fq) const {
;     ...
;             for (int ai = 0; ai < 2; ++ai)
; #pragma unroll
;                 for (int m = 0; m < 4; ++m) {
;                     const int row = row0 + ai * 128 + m * 16; const float rs = rsv[ai * 4 + m];
; #pragma unroll
;                     for (int bj = 0; bj < 2; ++bj) {
;                         const int cg = coff + ct + bj * 128;
;                         const f32x4 b0 = *(const f32x4*)(blr_b + cg), b1 = *(const f32x4*)(blr_b + cg + 4);
;                         f32x4 x0 = acc[ai][bj][m][0] * rs + b0, x1 = acc[ai][bj][m][1] * rs + b1;
; #pragma unroll
;                         for (int j = 0; j < 4; ++j) { x0[j] = (fminf(x0[j], 0.f) - __logf(1.f + __expf(-fabsf(x0[j])))) * (1.f / 16.f); x1[j] = (fminf(x1[j], 0.f) - __logf(1.f + __expf(-fabsf(x1[j])))) * (1.f / 16.f); }
;                         u32x4 w; w.x = cvt_pk_bf16(x0[0], x0[1]); w.y = cvt_pk_bf16(x0[2], x0[3]); w.z = cvt_pk_bf16(x1[0], x1[1]); w.w = cvt_pk_bf16(x1[2], x1[3]);
;                         *(u32x4*)(base + (size_t)row * 512 + cg) = w;
	v_pk_fma_f32 v[44:45], v[44:45], v[162:163], v[52:53] op_sel_hi:[1,0,1]
	v_pk_fma_f32 v[46:47], v[46:47], v[162:163], v[54:55] op_sel_hi:[1,0,1]
	v_mul_f32_e64 v41, |v44|, s25
	v_exp_f32_e32 v41, v41
	v_min_f32_e32 v40, 0, v44
	v_pk_fma_f32 v[42:43], v[42:43], v[162:163], v[50:51] op_sel_hi:[1,0,1]
	v_add_f32_e32 v41, 1.0, v41
	v_log_f32_e32 v41, v41
	s_nop 0
	v_mul_f32_e32 v44, 0x3f317217, v41
	v_fma_f32 v44, v41, s23, -v44
	v_fmac_f32_e32 v44, 0x3377d1cf, v41
	v_fmac_f32_e32 v44, 0x3f317217, v41
	v_mov_b32_e32 v41, v44
	v_mul_f32_e64 v44, |v48|, s25
	v_exp_f32_e32 v44, v44
	v_sub_f32_e32 v40, v40, v41
	v_min_f32_e32 v41, 0, v48
	v_mul_f32_e32 v40, 0x3d800000, v40
	v_add_f32_e32 v44, 1.0, v44
	v_log_f32_e32 v44, v44
	s_nop 0
	v_mul_f32_e32 v48, 0x3f317217, v44
	v_fma_f32 v48, v44, s23, -v48
	v_fmac_f32_e32 v48, 0x3377d1cf, v44
	v_fmac_f32_e32 v48, 0x3f317217, v44
	v_mov_b32_e32 v44, v48
	v_sub_f32_e32 v41, v41, v44
	v_min_f32_e32 v44, 0, v45
	v_mul_f32_e64 v45, |v45|, s25
	v_exp_f32_e32 v45, v45
	v_mul_f32_e32 v41, 0x3d800000, v41
	v_add_f32_e32 v45, 1.0, v45
	v_log_f32_e32 v45, v45
	s_nop 0
	v_mul_f32_e32 v48, 0x3f317217, v45
	v_fma_f32 v48, v45, s23, -v48
	v_fmac_f32_e32 v48, 0x3377d1cf, v45
	v_fmac_f32_e32 v48, 0x3f317217, v45
	v_mov_b32_e32 v45, v48
	v_mul_f32_e64 v48, |v49|, s25
	v_exp_f32_e32 v48, v48
	v_sub_f32_e32 v44, v44, v45
	v_min_f32_e32 v45, 0, v49
	v_mul_f32_e32 v44, 0x3d800000, v44
	v_add_f32_e32 v48, 1.0, v48
	v_log_f32_e32 v48, v48
	s_nop 0
	v_mul_f32_e32 v49, 0x3f317217, v48
	v_fma_f32 v49, v48, s23, -v49
	v_fmac_f32_e32 v49, 0x3377d1cf, v48
	v_fmac_f32_e32 v49, 0x3f317217, v48
	v_mov_b32_e32 v48, v49
	v_sub_f32_e32 v45, v45, v48
	v_min_f32_e32 v48, 0, v46
	v_mul_f32_e64 v46, |v46|, s25
	v_exp_f32_e32 v46, v46
	v_mul_f32_e32 v45, 0x3d800000, v45
	v_add_f32_e32 v46, 1.0, v46
	v_log_f32_e32 v46, v46
	s_nop 0
	v_mul_f32_e32 v49, 0x3f317217, v46
	v_fma_f32 v49, v46, s23, -v49
	v_fmac_f32_e32 v49, 0x3377d1cf, v46
	v_fmac_f32_e32 v49, 0x3f317217, v46
	v_mov_b32_e32 v46, v49
	v_sub_f32_e32 v46, v48, v46
	v_min_f32_e32 v48, 0, v42
	v_mul_f32_e64 v42, |v42|, s25
	v_exp_f32_e32 v42, v42
	v_mul_f32_e32 v46, 0x3d800000, v46
	v_add_f32_e32 v42, 1.0, v42
	v_log_f32_e32 v42, v42
	s_nop 0
	v_mul_f32_e32 v49, 0x3f317217, v42
	v_fma_f32 v49, v42, s23, -v49
	v_fmac_f32_e32 v49, 0x3377d1cf, v42
	v_fmac_f32_e32 v49, 0x3f317217, v42
	v_mov_b32_e32 v42, v49
	v_sub_f32_e32 v42, v48, v42
	v_mul_f32_e32 v48, 0x3d800000, v42
	v_min_f32_e32 v42, 0, v47
	v_mul_f32_e64 v47, |v47|, s25
	v_exp_f32_e32 v47, v47
	s_nop 0
	v_add_f32_e32 v47, 1.0, v47
	v_log_f32_e32 v47, v47
	s_nop 0
	v_mul_f32_e32 v49, 0x3f317217, v47
	v_fma_f32 v49, v47, s23, -v49
	v_fmac_f32_e32 v49, 0x3377d1cf, v47
	v_fmac_f32_e32 v49, 0x3f317217, v47
	v_mov_b32_e32 v47, v49
	v_sub_f32_e32 v42, v42, v47
	v_mul_f32_e32 v47, 0x3d800000, v42
	v_min_f32_e32 v42, 0, v43
	v_mul_f32_e64 v43, |v43|, s25
	v_exp_f32_e32 v43, v43
	s_nop 0
	v_add_f32_e32 v43, 1.0, v43
	v_log_f32_e32 v43, v43
	s_nop 0
	v_mul_f32_e32 v49, 0x3f317217, v43
	v_fma_f32 v49, v43, s23, -v49
	v_fmac_f32_e32 v49, 0x3377d1cf, v43
	v_fmac_f32_e32 v49, 0x3f317217, v43
	v_mov_b32_e32 v43, v49
	v_sub_f32_e32 v42, v42, v43
	s_mov_b64 s[0:1], 0x24000
	v_mul_f32_e32 v49, 0x3d800000, v42
	v_cvt_pk_bf16_f32 v42, v40, v44
	v_cvt_pk_bf16_f32 v43, v46, v47
	v_cvt_pk_bf16_f32 v44, v41, v45
	v_lshl_add_u64 v[40:41], v[120:121], 0, s[0:1]
	s_mov_b32 s0, 0x24000
	v_add_co_u32_e32 v46, vcc, s0, v120
	v_cvt_pk_bf16_f32 v45, v48, v49
	s_nop 1
	v_addc_co_u32_e32 v47, vcc, 0, v121, vcc
	global_store_dwordx4 v[46:47], v[42:45], off
	global_load_dwordx4 v[42:45], v[128:129], off offset:528
	s_nop 0
	global_load_dwordx4 v[46:49], v[128:129], off offset:512
	s_waitcnt vmcnt(1)
	v_pk_fma_f32 v[42:43], v[32:33], v[162:163], v[42:43] op_sel_hi:[1,0,1]
	s_waitcnt vmcnt(0)
	v_pk_fma_f32 v[36:37], v[36:37], v[162:163], v[46:47] op_sel_hi:[1,0,1]
	v_pk_fma_f32 v[38:39], v[38:39], v[162:163], v[48:49] op_sel_hi:[1,0,1]
	v_mul_f32_e64 v33, |v36|, s25
	v_exp_f32_e32 v33, v33
	v_min_f32_e32 v32, 0, v36
	v_pk_fma_f32 v[34:35], v[34:35], v[162:163], v[44:45] op_sel_hi:[1,0,1]
	v_add_f32_e32 v33, 1.0, v33
	v_log_f32_e32 v33, v33
	s_nop 0
	v_mul_f32_e32 v36, 0x3f317217, v33
	v_fma_f32 v36, v33, s23, -v36
	v_fmac_f32_e32 v36, 0x3377d1cf, v33
	v_fmac_f32_e32 v36, 0x3f317217, v33
	v_mov_b32_e32 v33, v36
	v_mul_f32_e64 v36, |v42|, s25
	v_exp_f32_e32 v36, v36
	v_sub_f32_e32 v32, v32, v33
	v_min_f32_e32 v33, 0, v42
	v_mul_f32_e32 v32, 0x3d800000, v32
	v_add_f32_e32 v36, 1.0, v36
	v_log_f32_e32 v36, v36
	s_nop 0
	v_mul_f32_e32 v42, 0x3f317217, v36
	v_fma_f32 v42, v36, s23, -v42
	v_fmac_f32_e32 v42, 0x3377d1cf, v36
	v_fmac_f32_e32 v42, 0x3f317217, v36
	v_mov_b32_e32 v36, v42
	v_sub_f32_e32 v33, v33, v36
	v_mul_f32_e32 v36, 0x3d800000, v33
	v_min_f32_e32 v33, 0, v37
	v_mul_f32_e64 v37, |v37|, s25
	v_exp_f32_e32 v37, v37
	s_nop 0
	v_add_f32_e32 v37, 1.0, v37
	v_log_f32_e32 v37, v37
	s_nop 0
	v_mul_f32_e32 v42, 0x3f317217, v37
	v_fma_f32 v42, v37, s23, -v42
	v_fmac_f32_e32 v42, 0x3377d1cf, v37
	v_fmac_f32_e32 v42, 0x3f317217, v37
	v_mov_b32_e32 v37, v42
	v_mul_f32_e64 v42, |v43|, s25
	v_exp_f32_e32 v42, v42
	v_sub_f32_e32 v33, v33, v37
	v_min_f32_e32 v37, 0, v43
	v_mul_f32_e32 v33, 0x3d800000, v33
	v_add_f32_e32 v42, 1.0, v42
	v_cvt_pk_bf16_f32 v32, v32, v33
	v_log_f32_e32 v42, v42
	s_nop 0
	v_mul_f32_e32 v43, 0x3f317217, v42
	v_fma_f32 v43, v42, s23, -v43
	v_fmac_f32_e32 v43, 0x3377d1cf, v42
	v_fmac_f32_e32 v43, 0x3f317217, v42
	v_mov_b32_e32 v42, v43
	v_sub_f32_e32 v37, v37, v42
	v_min_f32_e32 v42, 0, v38
	v_mul_f32_e64 v38, |v38|, s25
	v_exp_f32_e32 v38, v38
; __device__ __forceinline__ unsigned cvt_pk_bf16(float lo, float hi) { unsigned r; asm volatile("v_cvt_pk_bf16_f32 %0, %1, %2" : "=v"(r) : "v"(lo), "v"(hi)); return r; }
;     __device__ __forceinline__ void operator()(const AccT& acc, const pg8::Unit& u, int wr, int wc, int fr, int fq) const {
;     ...
;             for (int ai = 0; ai < 2; ++ai)
; #pragma unroll
;                 for (int m = 0; m < 4; ++m) {
;                     const int row = row0 + ai * 128 + m * 16; const float rs = rsv[ai * 4 + m];
; #pragma unroll
;                     for (int bj = 0; bj < 2; ++bj) {
;                         const int cg = coff + ct + bj * 128;
;                         const f32x4 b0 = *(const f32x4*)(blr_b + cg), b1 = *(const f32x4*)(blr_b + cg + 4);
;                         f32x4 x0 = acc[ai][bj][m][0] * rs + b0, x1 = acc[ai][bj][m][1] * rs + b1;
; #pragma unroll
;                         for (int j = 0; j < 4; ++j) { x0[j] = (fminf(x0[j], 0.f) - __logf(1.f + __expf(-fabsf(x0[j])))) * (1.f / 16.f); x1[j] = (fminf(x1[j], 0.f) - __logf(1.f + __expf(-fabsf(x1[j])))) * (1.f / 16.f); }
;                         u32x4 w; w.x = cvt_pk_bf16(x0[0], x0[1]); w.y = cvt_pk_bf16(x0[2], x0[3]); w.z = cvt_pk_bf16(x1[0], x1[1]); w.w = cvt_pk_bf16(x1[2], x1[3]);
;                         *(u32x4*)(base + (size_t)row * 512 + cg) = w;
	v_mul_f32_e32 v37, 0x3d800000, v37
	v_add_f32_e32 v38, 1.0, v38
	v_log_f32_e32 v38, v38
	s_nop 0
	v_mul_f32_e32 v43, 0x3f317217, v38
	v_fma_f32 v43, v38, s23, -v43
	v_fmac_f32_e32 v43, 0x3377d1cf, v38
	v_fmac_f32_e32 v43, 0x3f317217, v38
	v_mov_b32_e32 v38, v43
	v_sub_f32_e32 v38, v42, v38
	v_min_f32_e32 v42, 0, v34
	v_mul_f32_e64 v34, |v34|, s25
	v_exp_f32_e32 v34, v34
	v_mul_f32_e32 v38, 0x3d800000, v38
	v_add_f32_e32 v34, 1.0, v34
	v_log_f32_e32 v34, v34
	s_nop 0
	v_mul_f32_e32 v43, 0x3f317217, v34
	v_fma_f32 v43, v34, s23, -v43
	v_fmac_f32_e32 v43, 0x3377d1cf, v34
	v_fmac_f32_e32 v43, 0x3f317217, v34
	v_mov_b32_e32 v34, v43
	v_sub_f32_e32 v34, v42, v34
	v_mul_f32_e32 v42, 0x3d800000, v34
	v_min_f32_e32 v34, 0, v39
	v_mul_f32_e64 v39, |v39|, s25
	v_exp_f32_e32 v39, v39
	s_nop 0
	v_add_f32_e32 v39, 1.0, v39
	v_log_f32_e32 v39, v39
	s_nop 0
	v_mul_f32_e32 v43, 0x3f317217, v39
	v_fma_f32 v43, v39, s23, -v43
	v_fmac_f32_e32 v43, 0x3377d1cf, v39
	v_fmac_f32_e32 v43, 0x3f317217, v39
	v_mov_b32_e32 v39, v43
	v_sub_f32_e32 v34, v34, v39
	v_min_f32_e32 v39, 0, v35
	v_mul_f32_e64 v35, |v35|, s25
	v_exp_f32_e32 v35, v35
	v_mul_f32_e32 v34, 0x3d800000, v34
	v_cvt_pk_bf16_f32 v33, v38, v34
	v_cvt_pk_bf16_f32 v34, v36, v37
	v_add_f32_e32 v35, 1.0, v35
	v_log_f32_e32 v35, v35
	s_nop 0
	v_mul_f32_e32 v43, 0x3f317217, v35
	v_fma_f32 v43, v35, s23, -v43
	v_fmac_f32_e32 v43, 0x3377d1cf, v35
	v_fmac_f32_e32 v43, 0x3f317217, v35
	v_mov_b32_e32 v35, v43
	v_sub_f32_e32 v35, v39, v35
	v_mul_f32_e32 v35, 0x3d800000, v35
	v_cvt_pk_bf16_f32 v35, v42, v35
	global_store_dwordx4 v[40:41], v[32:35], off offset:256
	global_load_dwordx4 v[32:35], v[128:129], off offset:16
	s_nop 0
	global_load_dwordx4 v[36:39], v[128:129], off
	s_waitcnt vmcnt(1)
	v_pk_fma_f32 v[32:33], v[24:25], v[160:161], v[32:33] op_sel_hi:[1,0,1]
	s_waitcnt vmcnt(0)
	v_pk_fma_f32 v[28:29], v[28:29], v[160:161], v[36:37] op_sel_hi:[1,0,1]
	v_pk_fma_f32 v[30:31], v[30:31], v[160:161], v[38:39] op_sel_hi:[1,0,1]
	v_mul_f32_e64 v25, |v28|, s25
	v_exp_f32_e32 v25, v25
	v_min_f32_e32 v24, 0, v28
	v_pk_fma_f32 v[26:27], v[26:27], v[160:161], v[34:35] op_sel_hi:[1,0,1]
	v_add_f32_e32 v25, 1.0, v25
	v_log_f32_e32 v25, v25
	s_nop 0
	v_mul_f32_e32 v28, 0x3f317217, v25
	v_fma_f32 v28, v25, s23, -v28
	v_fmac_f32_e32 v28, 0x3377d1cf, v25
	v_fmac_f32_e32 v28, 0x3f317217, v25
	v_mov_b32_e32 v25, v28
	v_mul_f32_e64 v28, |v32|, s25
	v_exp_f32_e32 v28, v28
	v_sub_f32_e32 v24, v24, v25
	v_min_f32_e32 v25, 0, v32
	v_mul_f32_e32 v24, 0x3d800000, v24
	v_add_f32_e32 v28, 1.0, v28
	v_log_f32_e32 v28, v28
	s_nop 0
	v_mul_f32_e32 v32, 0x3f317217, v28
	v_fma_f32 v32, v28, s23, -v32
	v_fmac_f32_e32 v32, 0x3377d1cf, v28
	v_fmac_f32_e32 v32, 0x3f317217, v28
	v_mov_b32_e32 v28, v32
	v_sub_f32_e32 v25, v25, v28
	v_min_f32_e32 v28, 0, v29
	v_mul_f32_e64 v29, |v29|, s25
	v_exp_f32_e32 v29, v29
	v_mul_f32_e32 v25, 0x3d800000, v25
	v_add_f32_e32 v29, 1.0, v29
	v_log_f32_e32 v29, v29
	s_nop 0
	v_mul_f32_e32 v32, 0x3f317217, v29
	v_fma_f32 v32, v29, s23, -v32
	v_fmac_f32_e32 v32, 0x3377d1cf, v29
	v_fmac_f32_e32 v32, 0x3f317217, v29
	v_mov_b32_e32 v29, v32
	v_mul_f32_e64 v32, |v33|, s25
	v_exp_f32_e32 v32, v32
	v_sub_f32_e32 v28, v28, v29
	v_min_f32_e32 v29, 0, v33
	v_mul_f32_e32 v28, 0x3d800000, v28
	v_add_f32_e32 v32, 1.0, v32
	v_log_f32_e32 v32, v32
	s_nop 0
	v_mul_f32_e32 v33, 0x3f317217, v32
	v_fma_f32 v33, v32, s23, -v33
	v_fmac_f32_e32 v33, 0x3377d1cf, v32
	v_fmac_f32_e32 v33, 0x3f317217, v32
	v_mov_b32_e32 v32, v33
	v_sub_f32_e32 v29, v29, v32
	v_min_f32_e32 v32, 0, v30
	v_mul_f32_e64 v30, |v30|, s25
	v_exp_f32_e32 v30, v30
	v_mul_f32_e32 v29, 0x3d800000, v29
	v_add_f32_e32 v30, 1.0, v30
	v_log_f32_e32 v30, v30
	s_nop 0
	v_mul_f32_e32 v33, 0x3f317217, v30
	v_fma_f32 v33, v30, s23, -v33
	v_fmac_f32_e32 v33, 0x3377d1cf, v30
	v_fmac_f32_e32 v33, 0x3f317217, v30
	v_mov_b32_e32 v30, v33
	v_sub_f32_e32 v30, v32, v30
	v_min_f32_e32 v32, 0, v26
	v_mul_f32_e64 v26, |v26|, s25
	v_exp_f32_e32 v26, v26
	v_mul_f32_e32 v30, 0x3d800000, v30
	v_add_f32_e32 v26, 1.0, v26
	v_log_f32_e32 v26, v26
	s_nop 0
	v_mul_f32_e32 v33, 0x3f317217, v26
	v_fma_f32 v33, v26, s23, -v33
	v_fmac_f32_e32 v33, 0x3377d1cf, v26
	v_fmac_f32_e32 v33, 0x3f317217, v26
	v_mov_b32_e32 v26, v33
	v_sub_f32_e32 v26, v32, v26
	v_mul_f32_e32 v32, 0x3d800000, v26
	v_min_f32_e32 v26, 0, v31
	v_mul_f32_e64 v31, |v31|, s25
	v_exp_f32_e32 v31, v31
	s_nop 0
	v_add_f32_e32 v31, 1.0, v31
	v_log_f32_e32 v31, v31
	s_nop 0
	v_mul_f32_e32 v33, 0x3f317217, v31
	v_fma_f32 v33, v31, s23, -v33
	v_fmac_f32_e32 v33, 0x3377d1cf, v31
	v_fmac_f32_e32 v33, 0x3f317217, v31
	v_mov_b32_e32 v31, v33
	v_sub_f32_e32 v26, v26, v31
	v_mul_f32_e32 v31, 0x3d800000, v26
	v_min_f32_e32 v26, 0, v27
	v_mul_f32_e64 v27, |v27|, s25
	v_exp_f32_e32 v27, v27
	s_nop 0
	v_add_f32_e32 v27, 1.0, v27
	v_log_f32_e32 v27, v27
	s_nop 0
	v_mul_f32_e32 v33, 0x3f317217, v27
	v_fma_f32 v33, v27, s23, -v33
	v_fmac_f32_e32 v33, 0x3377d1cf, v27
	v_fmac_f32_e32 v33, 0x3f317217, v27
	v_mov_b32_e32 v27, v33
	v_sub_f32_e32 v26, v26, v27
	s_mov_b64 s[0:1], 0x28000
	v_mul_f32_e32 v33, 0x3d800000, v26
	v_cvt_pk_bf16_f32 v26, v24, v28
	v_cvt_pk_bf16_f32 v27, v30, v31
	v_cvt_pk_bf16_f32 v28, v25, v29
	v_lshl_add_u64 v[24:25], v[120:121], 0, s[0:1]
	s_mov_b32 s0, 0x28000
	v_add_co_u32_e32 v30, vcc, s0, v120
	v_cvt_pk_bf16_f32 v29, v32, v33
	s_nop 1
	v_addc_co_u32_e32 v31, vcc, 0, v121, vcc
	global_store_dwordx4 v[30:31], v[26:29], off
	global_load_dwordx4 v[26:29], v[128:129], off offset:528
	s_nop 0
	global_load_dwordx4 v[30:33], v[128:129], off offset:512
	s_waitcnt vmcnt(1)
	v_pk_fma_f32 v[26:27], v[16:17], v[160:161], v[26:27] op_sel_hi:[1,0,1]
	s_waitcnt vmcnt(0)
; __device__ __forceinline__ unsigned cvt_pk_bf16(float lo, float hi) { unsigned r; asm volatile("v_cvt_pk_bf16_f32 %0, %1, %2" : "=v"(r) : "v"(lo), "v"(hi)); return r; }
;     __device__ __forceinline__ void operator()(const AccT& acc, const pg8::Unit& u, int wr, int wc, int fr, int fq) const {
;     ...
;             for (int ai = 0; ai < 2; ++ai)
; #pragma unroll
;                 for (int m = 0; m < 4; ++m) {
;                     const int row = row0 + ai * 128 + m * 16; const float rs = rsv[ai * 4 + m];
; #pragma unroll
;                     for (int bj = 0; bj < 2; ++bj) {
;                         const int cg = coff + ct + bj * 128;
;                         const f32x4 b0 = *(const f32x4*)(blr_b + cg), b1 = *(const f32x4*)(blr_b + cg + 4);
;                         f32x4 x0 = acc[ai][bj][m][0] * rs + b0, x1 = acc[ai][bj][m][1] * rs + b1;
; #pragma unroll
;                         for (int j = 0; j < 4; ++j) { x0[j] = (fminf(x0[j], 0.f) - __logf(1.f + __expf(-fabsf(x0[j])))) * (1.f / 16.f); x1[j] = (fminf(x1[j], 0.f) - __logf(1.f + __expf(-fabsf(x1[j])))) * (1.f / 16.f); }
;                         u32x4 w; w.x = cvt_pk_bf16(x0[0], x0[1]); w.y = cvt_pk_bf16(x0[2], x0[3]); w.z = cvt_pk_bf16(x1[0], x1[1]); w.w = cvt_pk_bf16(x1[2], x1[3]);
;                         *(u32x4*)(base + (size_t)row * 512 + cg) = w;
	v_pk_fma_f32 v[20:21], v[20:21], v[160:161], v[30:31] op_sel_hi:[1,0,1]
	v_pk_fma_f32 v[22:23], v[22:23], v[160:161], v[32:33] op_sel_hi:[1,0,1]
	v_mul_f32_e64 v17, |v20|, s25
	v_exp_f32_e32 v17, v17
	v_min_f32_e32 v16, 0, v20
	v_pk_fma_f32 v[18:19], v[18:19], v[160:161], v[28:29] op_sel_hi:[1,0,1]
	v_add_f32_e32 v17, 1.0, v17
	v_log_f32_e32 v17, v17
	s_nop 0
	v_mul_f32_e32 v20, 0x3f317217, v17
	v_fma_f32 v20, v17, s23, -v20
	v_fmac_f32_e32 v20, 0x3377d1cf, v17
	v_fmac_f32_e32 v20, 0x3f317217, v17
	v_mov_b32_e32 v17, v20
	v_mul_f32_e64 v20, |v26|, s25
	v_exp_f32_e32 v20, v20
	v_sub_f32_e32 v16, v16, v17
	v_min_f32_e32 v17, 0, v26
	v_mul_f32_e32 v16, 0x3d800000, v16
	v_add_f32_e32 v20, 1.0, v20
	v_log_f32_e32 v20, v20
	s_nop 0
	v_mul_f32_e32 v26, 0x3f317217, v20
	v_fma_f32 v26, v20, s23, -v26
	v_fmac_f32_e32 v26, 0x3377d1cf, v20
	v_fmac_f32_e32 v26, 0x3f317217, v20
	v_mov_b32_e32 v20, v26
	v_sub_f32_e32 v17, v17, v20
	v_mul_f32_e32 v20, 0x3d800000, v17
	v_min_f32_e32 v17, 0, v21
	v_mul_f32_e64 v21, |v21|, s25
	v_exp_f32_e32 v21, v21
	s_nop 0
	v_add_f32_e32 v21, 1.0, v21
	v_log_f32_e32 v21, v21
	s_nop 0
	v_mul_f32_e32 v26, 0x3f317217, v21
	v_fma_f32 v26, v21, s23, -v26
	v_fmac_f32_e32 v26, 0x3377d1cf, v21
	v_fmac_f32_e32 v26, 0x3f317217, v21
	v_mov_b32_e32 v21, v26
	v_mul_f32_e64 v26, |v27|, s25
	v_exp_f32_e32 v26, v26
	v_sub_f32_e32 v17, v17, v21
	v_min_f32_e32 v21, 0, v27
	v_mul_f32_e32 v17, 0x3d800000, v17
	v_add_f32_e32 v26, 1.0, v26
	v_cvt_pk_bf16_f32 v16, v16, v17
	v_log_f32_e32 v26, v26
	s_nop 0
	v_mul_f32_e32 v27, 0x3f317217, v26
	v_fma_f32 v27, v26, s23, -v27
	v_fmac_f32_e32 v27, 0x3377d1cf, v26
	v_fmac_f32_e32 v27, 0x3f317217, v26
	v_mov_b32_e32 v26, v27
	v_sub_f32_e32 v21, v21, v26
	v_min_f32_e32 v26, 0, v22
	v_mul_f32_e64 v22, |v22|, s25
	v_exp_f32_e32 v22, v22
	v_mul_f32_e32 v21, 0x3d800000, v21
	v_add_f32_e32 v22, 1.0, v22
	v_log_f32_e32 v22, v22
	s_nop 0
	v_mul_f32_e32 v27, 0x3f317217, v22
	v_fma_f32 v27, v22, s23, -v27
	v_fmac_f32_e32 v27, 0x3377d1cf, v22
	v_fmac_f32_e32 v27, 0x3f317217, v22
	v_mov_b32_e32 v22, v27
	v_sub_f32_e32 v22, v26, v22
	v_min_f32_e32 v26, 0, v18
	v_mul_f32_e64 v18, |v18|, s25
	v_exp_f32_e32 v18, v18
	v_mul_f32_e32 v22, 0x3d800000, v22
	v_add_f32_e32 v18, 1.0, v18
	v_log_f32_e32 v18, v18
	s_nop 0
	v_mul_f32_e32 v27, 0x3f317217, v18
	v_fma_f32 v27, v18, s23, -v27
	v_fmac_f32_e32 v27, 0x3377d1cf, v18
	v_fmac_f32_e32 v27, 0x3f317217, v18
	v_mov_b32_e32 v18, v27
	v_sub_f32_e32 v18, v26, v18
	v_mul_f32_e32 v26, 0x3d800000, v18
	v_min_f32_e32 v18, 0, v23
	v_mul_f32_e64 v23, |v23|, s25
	v_exp_f32_e32 v23, v23
	s_nop 0
	v_add_f32_e32 v23, 1.0, v23
	v_log_f32_e32 v23, v23
	s_nop 0
	v_mul_f32_e32 v27, 0x3f317217, v23
	v_fma_f32 v27, v23, s23, -v27
	v_fmac_f32_e32 v27, 0x3377d1cf, v23
	v_fmac_f32_e32 v27, 0x3f317217, v23
	v_mov_b32_e32 v23, v27
	v_sub_f32_e32 v18, v18, v23
	v_min_f32_e32 v23, 0, v19
	v_mul_f32_e64 v19, |v19|, s25
	v_exp_f32_e32 v19, v19
	v_mul_f32_e32 v18, 0x3d800000, v18
	v_cvt_pk_bf16_f32 v17, v22, v18
	v_cvt_pk_bf16_f32 v18, v20, v21
	v_add_f32_e32 v19, 1.0, v19
	v_log_f32_e32 v19, v19
	s_nop 0
	v_mul_f32_e32 v27, 0x3f317217, v19
	v_fma_f32 v27, v19, s23, -v27
	v_fmac_f32_e32 v27, 0x3377d1cf, v19
	v_fmac_f32_e32 v27, 0x3f317217, v19
	v_mov_b32_e32 v19, v27
	v_sub_f32_e32 v19, v23, v19
	v_mul_f32_e32 v19, 0x3d800000, v19
	v_cvt_pk_bf16_f32 v19, v26, v19
	global_store_dwordx4 v[24:25], v[16:19], off offset:256
	global_load_dwordx4 v[16:19], v[128:129], off offset:16
	s_nop 0
	global_load_dwordx4 v[20:23], v[128:129], off
	s_waitcnt vmcnt(1)
	v_pk_fma_f32 v[16:17], v[8:9], v[158:159], v[16:17] op_sel_hi:[1,0,1]
	s_waitcnt vmcnt(0)
	v_pk_fma_f32 v[12:13], v[12:13], v[158:159], v[20:21] op_sel_hi:[1,0,1]
	v_pk_fma_f32 v[14:15], v[14:15], v[158:159], v[22:23] op_sel_hi:[1,0,1]
	v_mul_f32_e64 v9, |v12|, s25
	v_exp_f32_e32 v9, v9
	v_min_f32_e32 v8, 0, v12
	v_pk_fma_f32 v[10:11], v[10:11], v[158:159], v[18:19] op_sel_hi:[1,0,1]
	v_add_f32_e32 v9, 1.0, v9
	v_log_f32_e32 v9, v9
	s_nop 0
	v_mul_f32_e32 v12, 0x3f317217, v9
	v_fma_f32 v12, v9, s23, -v12
	v_fmac_f32_e32 v12, 0x3377d1cf, v9
	v_fmac_f32_e32 v12, 0x3f317217, v9
	v_mov_b32_e32 v9, v12
	v_mul_f32_e64 v12, |v16|, s25
	v_exp_f32_e32 v12, v12
	v_sub_f32_e32 v8, v8, v9
	v_min_f32_e32 v9, 0, v16
	v_mul_f32_e32 v8, 0x3d800000, v8
	v_add_f32_e32 v12, 1.0, v12
	v_log_f32_e32 v12, v12
	s_nop 0
	v_mul_f32_e32 v16, 0x3f317217, v12
	v_fma_f32 v16, v12, s23, -v16
	v_fmac_f32_e32 v16, 0x3377d1cf, v12
	v_fmac_f32_e32 v16, 0x3f317217, v12
	v_mov_b32_e32 v12, v16
	v_sub_f32_e32 v9, v9, v12
	v_min_f32_e32 v12, 0, v13
	v_mul_f32_e64 v13, |v13|, s25
	v_exp_f32_e32 v13, v13
	v_mul_f32_e32 v9, 0x3d800000, v9
	v_add_f32_e32 v13, 1.0, v13
	v_log_f32_e32 v13, v13
	s_nop 0
	v_mul_f32_e32 v16, 0x3f317217, v13
	v_fma_f32 v16, v13, s23, -v16
	v_fmac_f32_e32 v16, 0x3377d1cf, v13
	v_fmac_f32_e32 v16, 0x3f317217, v13
	v_mov_b32_e32 v13, v16
	v_mul_f32_e64 v16, |v17|, s25
	v_exp_f32_e32 v16, v16
	v_sub_f32_e32 v12, v12, v13
	v_min_f32_e32 v13, 0, v17
	v_mul_f32_e32 v12, 0x3d800000, v12
	v_add_f32_e32 v16, 1.0, v16
	v_log_f32_e32 v16, v16
	s_nop 0
	v_mul_f32_e32 v17, 0x3f317217, v16
	v_fma_f32 v17, v16, s23, -v17
	v_fmac_f32_e32 v17, 0x3377d1cf, v16
	v_fmac_f32_e32 v17, 0x3f317217, v16
	v_mov_b32_e32 v16, v17
	v_sub_f32_e32 v13, v13, v16
	v_min_f32_e32 v16, 0, v14
	v_mul_f32_e64 v14, |v14|, s25
	v_exp_f32_e32 v14, v14
; __device__ __forceinline__ unsigned cvt_pk_bf16(float lo, float hi) { unsigned r; asm volatile("v_cvt_pk_bf16_f32 %0, %1, %2" : "=v"(r) : "v"(lo), "v"(hi)); return r; }
;     __device__ __forceinline__ void operator()(const AccT& acc, const pg8::Unit& u, int wr, int wc, int fr, int fq) const {
;     ...
;             for (int ai = 0; ai < 2; ++ai)
; #pragma unroll
;                 for (int m = 0; m < 4; ++m) {
;                     const int row = row0 + ai * 128 + m * 16; const float rs = rsv[ai * 4 + m];
; #pragma unroll
;                     for (int bj = 0; bj < 2; ++bj) {
;                         const int cg = coff + ct + bj * 128;
;                         const f32x4 b0 = *(const f32x4*)(blr_b + cg), b1 = *(const f32x4*)(blr_b + cg + 4);
;                         f32x4 x0 = acc[ai][bj][m][0] * rs + b0, x1 = acc[ai][bj][m][1] * rs + b1;
; #pragma unroll
;                         for (int j = 0; j < 4; ++j) { x0[j] = (fminf(x0[j], 0.f) - __logf(1.f + __expf(-fabsf(x0[j])))) * (1.f / 16.f); x1[j] = (fminf(x1[j], 0.f) - __logf(1.f + __expf(-fabsf(x1[j])))) * (1.f / 16.f); }
;                         u32x4 w; w.x = cvt_pk_bf16(x0[0], x0[1]); w.y = cvt_pk_bf16(x0[2], x0[3]); w.z = cvt_pk_bf16(x1[0], x1[1]); w.w = cvt_pk_bf16(x1[2], x1[3]);
;                         *(u32x4*)(base + (size_t)row * 512 + cg) = w;
	v_mul_f32_e32 v13, 0x3d800000, v13
	v_add_f32_e32 v14, 1.0, v14
	v_log_f32_e32 v14, v14
	s_nop 0
	v_mul_f32_e32 v17, 0x3f317217, v14
	v_fma_f32 v17, v14, s23, -v17
	v_fmac_f32_e32 v17, 0x3377d1cf, v14
	v_fmac_f32_e32 v17, 0x3f317217, v14
	v_mov_b32_e32 v14, v17
	v_sub_f32_e32 v14, v16, v14
	v_min_f32_e32 v16, 0, v10
	v_mul_f32_e64 v10, |v10|, s25
	v_exp_f32_e32 v10, v10
	v_mul_f32_e32 v14, 0x3d800000, v14
	v_add_f32_e32 v10, 1.0, v10
	v_log_f32_e32 v10, v10
	s_nop 0
	v_mul_f32_e32 v17, 0x3f317217, v10
	v_fma_f32 v17, v10, s23, -v17
	v_fmac_f32_e32 v17, 0x3377d1cf, v10
	v_fmac_f32_e32 v17, 0x3f317217, v10
	v_mov_b32_e32 v10, v17
	v_sub_f32_e32 v10, v16, v10
	v_mul_f32_e32 v16, 0x3d800000, v10
	v_min_f32_e32 v10, 0, v15
	v_mul_f32_e64 v15, |v15|, s25
	v_exp_f32_e32 v15, v15
	s_nop 0
	v_add_f32_e32 v15, 1.0, v15
	v_log_f32_e32 v15, v15
	s_nop 0
	v_mul_f32_e32 v17, 0x3f317217, v15
	v_fma_f32 v17, v15, s23, -v17
	v_fmac_f32_e32 v17, 0x3377d1cf, v15
	v_fmac_f32_e32 v17, 0x3f317217, v15
	v_mov_b32_e32 v15, v17
	v_sub_f32_e32 v10, v10, v15
	v_mul_f32_e32 v15, 0x3d800000, v10
	v_min_f32_e32 v10, 0, v11
	v_mul_f32_e64 v11, |v11|, s25
	v_exp_f32_e32 v11, v11
	s_nop 0
	v_add_f32_e32 v11, 1.0, v11
	v_log_f32_e32 v11, v11
	s_nop 0
	v_mul_f32_e32 v17, 0x3f317217, v11
	v_fma_f32 v17, v11, s23, -v17
	v_fmac_f32_e32 v17, 0x3377d1cf, v11
	v_fmac_f32_e32 v17, 0x3f317217, v11
	v_mov_b32_e32 v11, v17
	v_sub_f32_e32 v10, v10, v11
	s_mov_b64 s[0:1], 0x2c000
	v_mul_f32_e32 v17, 0x3d800000, v10
	v_cvt_pk_bf16_f32 v10, v8, v12
	v_cvt_pk_bf16_f32 v11, v14, v15
	v_cvt_pk_bf16_f32 v12, v9, v13
	v_lshl_add_u64 v[8:9], v[120:121], 0, s[0:1]
	s_mov_b32 s0, 0x2c000
	v_add_co_u32_e32 v14, vcc, s0, v120
	v_cvt_pk_bf16_f32 v13, v16, v17
	s_nop 1
	v_addc_co_u32_e32 v15, vcc, 0, v121, vcc
	global_store_dwordx4 v[14:15], v[10:13], off
	global_load_dwordx4 v[10:13], v[128:129], off offset:528
	s_nop 0
	global_load_dwordx4 v[14:17], v[128:129], off offset:512
	s_waitcnt vmcnt(1)
	v_pk_fma_f32 v[10:11], v[0:1], v[158:159], v[10:11] op_sel_hi:[1,0,1]
	s_waitcnt vmcnt(0)
	v_pk_fma_f32 v[4:5], v[4:5], v[158:159], v[14:15] op_sel_hi:[1,0,1]
	v_pk_fma_f32 v[6:7], v[6:7], v[158:159], v[16:17] op_sel_hi:[1,0,1]
	v_mul_f32_e64 v1, |v4|, s25
	v_exp_f32_e32 v1, v1
	v_min_f32_e32 v0, 0, v4
	v_pk_fma_f32 v[2:3], v[2:3], v[158:159], v[12:13] op_sel_hi:[1,0,1]
	v_add_f32_e32 v1, 1.0, v1
	v_log_f32_e32 v1, v1
	s_nop 0
	v_mul_f32_e32 v4, 0x3f317217, v1
	v_fma_f32 v4, v1, s23, -v4
	v_fmac_f32_e32 v4, 0x3377d1cf, v1
	v_fmac_f32_e32 v4, 0x3f317217, v1
	v_mov_b32_e32 v1, v4
	v_mul_f32_e64 v4, |v10|, s25
	v_exp_f32_e32 v4, v4
	v_sub_f32_e32 v0, v0, v1
	v_min_f32_e32 v1, 0, v10
	v_mul_f32_e32 v0, 0x3d800000, v0
	v_add_f32_e32 v4, 1.0, v4
	v_log_f32_e32 v4, v4
	s_nop 0
	v_mul_f32_e32 v10, 0x3f317217, v4
	v_fma_f32 v10, v4, s23, -v10
	v_fmac_f32_e32 v10, 0x3377d1cf, v4
	v_fmac_f32_e32 v10, 0x3f317217, v4
	v_mov_b32_e32 v4, v10
	v_sub_f32_e32 v1, v1, v4
	v_mul_f32_e32 v4, 0x3d800000, v1
	v_min_f32_e32 v1, 0, v5
	v_mul_f32_e64 v5, |v5|, s25
	v_exp_f32_e32 v5, v5
	s_nop 0
	v_add_f32_e32 v5, 1.0, v5
	v_log_f32_e32 v5, v5
	s_nop 0
	v_mul_f32_e32 v10, 0x3f317217, v5
	v_fma_f32 v10, v5, s23, -v10
	v_fmac_f32_e32 v10, 0x3377d1cf, v5
	v_fmac_f32_e32 v10, 0x3f317217, v5
	v_mov_b32_e32 v5, v10
	v_mul_f32_e64 v10, |v11|, s25
	v_exp_f32_e32 v10, v10
	v_sub_f32_e32 v1, v1, v5
	v_min_f32_e32 v5, 0, v11
	v_mul_f32_e32 v1, 0x3d800000, v1
	v_add_f32_e32 v10, 1.0, v10
	v_cvt_pk_bf16_f32 v0, v0, v1
	v_log_f32_e32 v10, v10
	s_nop 0
	v_mul_f32_e32 v11, 0x3f317217, v10
	v_fma_f32 v11, v10, s23, -v11
	v_fmac_f32_e32 v11, 0x3377d1cf, v10
	v_fmac_f32_e32 v11, 0x3f317217, v10
	v_mov_b32_e32 v10, v11
	v_sub_f32_e32 v5, v5, v10
	v_min_f32_e32 v10, 0, v6
	v_mul_f32_e64 v6, |v6|, s25
	v_exp_f32_e32 v6, v6
	v_mul_f32_e32 v5, 0x3d800000, v5
	v_add_f32_e32 v6, 1.0, v6
	v_log_f32_e32 v6, v6
	s_nop 0
	v_mul_f32_e32 v11, 0x3f317217, v6
	v_fma_f32 v11, v6, s23, -v11
	v_fmac_f32_e32 v11, 0x3377d1cf, v6
	v_fmac_f32_e32 v11, 0x3f317217, v6
	v_mov_b32_e32 v6, v11
	v_sub_f32_e32 v6, v10, v6
	v_min_f32_e32 v10, 0, v2
	v_mul_f32_e64 v2, |v2|, s25
	v_exp_f32_e32 v2, v2
	v_mul_f32_e32 v6, 0x3d800000, v6
	v_add_f32_e32 v2, 1.0, v2
	v_log_f32_e32 v2, v2
	s_nop 0
	v_mul_f32_e32 v11, 0x3f317217, v2
	v_fma_f32 v11, v2, s23, -v11
	v_fmac_f32_e32 v11, 0x3377d1cf, v2
	v_fmac_f32_e32 v11, 0x3f317217, v2
	v_mov_b32_e32 v2, v11
	v_sub_f32_e32 v2, v10, v2
	v_mul_f32_e32 v10, 0x3d800000, v2
	v_min_f32_e32 v2, 0, v7
	v_mul_f32_e64 v7, |v7|, s25
	v_exp_f32_e32 v7, v7
	s_nop 0
	v_add_f32_e32 v7, 1.0, v7
	v_log_f32_e32 v7, v7
	s_nop 0
	v_mul_f32_e32 v11, 0x3f317217, v7
	v_fma_f32 v11, v7, s23, -v11
	v_fmac_f32_e32 v11, 0x3377d1cf, v7
	v_fmac_f32_e32 v11, 0x3f317217, v7
	v_mov_b32_e32 v7, v11
	v_sub_f32_e32 v2, v2, v7
	v_min_f32_e32 v7, 0, v3
	v_mul_f32_e64 v3, |v3|, s25
	v_exp_f32_e32 v3, v3
	v_mul_f32_e32 v2, 0x3d800000, v2
	v_cvt_pk_bf16_f32 v1, v6, v2
	v_cvt_pk_bf16_f32 v2, v4, v5
	v_add_f32_e32 v3, 1.0, v3
	v_log_f32_e32 v3, v3
	s_nop 0
	v_mul_f32_e32 v11, 0x3f317217, v3
	v_fma_f32 v11, v3, s23, -v11
	v_fmac_f32_e32 v11, 0x3377d1cf, v3
	v_fmac_f32_e32 v11, 0x3f317217, v3
	v_mov_b32_e32 v3, v11
	v_sub_f32_e32 v3, v7, v3
	v_mul_f32_e32 v3, 0x3d800000, v3
	v_cvt_pk_bf16_f32 v3, v10, v3
	global_store_dwordx4 v[8:9], v[0:3], off offset:256
	s_andn2_b64 vcc, exec, s[4:5]
	s_mov_b64 s[0:1], -1
	s_cbranch_vccnz .LBB0_118
